# fused tile128 pipes (MoBA, NSA-sel, NSA-win): O accumulators kept in v[0:31], copies + nops removed; on top of DIFF copy elimination
# speedup vs baseline: 1.0177x; 1.0018x over previous
; #define LAS __attribute__((address_space(3)))
; #define ST2_LOAD(T0) do { const int t0_ = (T0), t1_ = (t0_ + 1 > kt_hi) ? kt_hi : t0_ + 1; \
;         const size_t a0_ = (size_t)(64 * t0_ + skey) * pitch + 8 * sc, a1_ = (size_t)(64 * t1_ + skey) * pitch + 8 * sc; \
;         st.k0 = *(const u32x4*)(Kg + a0_); st.v0 = *(const u32x4*)(Vg + a0_); st.k1 = *(const u32x4*)(Kg + a1_); st.v1 = *(const u32x4*)(Vg + a1_); } while (0)
; template <int MM> DI void tile128_pipe(LAS const char* K0, LAS const char* V0, LAS const char* K1, LAS const char* V1, const bf16x8 (&qf)[4], unsigned vm0, unsigned vm1,
;                                        float& m, float& l, f32x16 (&o)[2], int r, int h, int lane) {
;     f32x16 sa = qk_rows<0, 4>(K0, 0, qf, r, h), sb = qk_rows<0, 4>(K0, 32, qf, r, h);
;     bf16x8 pfa[2], pfb[2];
;     smax_step_nb<MM>(sa, vm0, m, l, o, pfa, lane);
;     sa = qk_rows<0, 4>(K1, 0, qf, r, h);
; template <int MODE, bool PRE = false> ...
;     ...
;         if (sti + 1 < nst) ST2_LOAD(kt_lo + 2 * (sti + 1));
;         if (MODE != MODE_DIFF) {
;             const int kt0 = kt_lo + 2 * sti;
;             bool both = (kt0 + 1 <= kt_hi) && (64 * kt0 + 127 <= q0w);
;             if (MODE == MODE_NWIN) both = both && (64 * kt0 > q0w + 31 - 512);
;             if (both) {
;                 bool ls0 = true, ls1 = true;
;                 if (MODE == MODE_MOBA) { ls0 = ((sel >> (kt0 >> 2)) & 1ull) != 0ull; ls1 = ((sel >> ((kt0 + 1) >> 2)) & 1ull) != 0ull; }
;                 if (MODE == MODE_NSEL) { ls0 = ((sel >> kt0) & 1ull) != 0ull; ls1 = ((sel >> (kt0 + 1)) & 1ull) != 0ull; }
;                 const unsigned long long b0 = __builtin_amdgcn_ballot_w64(ls0), b1 = __builtin_amdgcn_ballot_w64(ls1);
;                 if (b0 != 0ull && b1 != 0ull) {
;                     LAS char* K0 = lds + (sti & 1) * 4 * TILE_B;
;                     if ((b0 & b1) == ~0ull) tile128_pipe<0>(K0, K0 + TILE_B, K0 + 2 * TILE_B, K0 + 3 * TILE_B, qf, 1u, 1u, m1, l1, o1, r, h, lane);
;                     else tile128_pipe<1>(K0, K0 + TILE_B, K0 + 2 * TILE_B, K0 + 3 * TILE_B, qf, ls0 ? 1u : 0u, ls1 ? 1u : 0u, m1, l1, o1, r, h, lane);
;                     goto step_done;
.LBB0_589:
	s_lshl_b32 s64, s48, 1
	s_cmp_lt_u32 s64, s58
	s_cselect_b64 s[0:1], -1, 0
	s_lshl_b32 s10, s48, 7
	s_or_b32 s10, s10, 0x7f
	s_cmp_le_i32 s10, s59
	s_cselect_b64 s[10:11], -1, 0
	s_and_b64 s[0:1], s[0:1], s[10:11]
	s_andn2_b64 vcc, exec, s[0:1]
	s_mov_b32 s10, 0
	s_cbranch_vccnz .LBB0_612
	s_or_b32 s0, s64, 1
	v_lshrrev_b64 v[32:33], s64, v[164:165]
	v_and_b32_e32 v34, 1, v32
	v_lshrrev_b64 v[32:33], s0, v[164:165]
	v_and_b32_e32 v32, 1, v32
	v_cmp_ne_u32_e64 s[40:41], 0, v34
	v_cmp_ne_u32_e64 s[42:43], 0, v32
	s_cmp_eq_u64 s[40:41], 0
	s_cselect_b64 s[34:35], -1, 0
	s_cmp_eq_u64 s[42:43], 0
	s_cselect_b64 s[56:57], -1, 0
	s_or_b64 s[34:35], s[34:35], s[56:57]
	v_cmp_eq_u32_e64 s[38:39], 1, v34
	v_cmp_eq_u32_e64 s[0:1], 1, v32
	s_and_b64 vcc, exec, s[34:35]
	s_cbranch_vccnz .LBB0_612
	s_lshl_b32 s10, s48, 2
	s_and_b32 s10, s10, 4
	s_mulk_i32 s10, 0x2400
	s_add_i32 s10, s10, 0
	v_add_u32_e32 v32, s10, v190
	v_add_u32_e32 v215, v32, v168
	s_waitcnt lgkmcnt(7)
	ds_read_b128 v[140:143], v215
	s_waitcnt lgkmcnt(7)
	ds_read_b128 v[136:139], v215 offset:32
	s_waitcnt lgkmcnt(7)
	ds_read_b128 v[132:135], v215 offset:64
	s_waitcnt lgkmcnt(7)
	ds_read_b128 v[128:131], v215 offset:96
	s_and_b64 s[34:35], s[42:43], s[40:41]
	s_cmp_lg_u64 s[34:35], -1
	s_setprio 1
	s_setprio 0
	s_waitcnt lgkmcnt(7)
	ds_read_b128 v[144:147], v215 offset:4608
	s_waitcnt lgkmcnt(7)
	ds_read_b128 v[148:151], v215 offset:4640
	s_waitcnt lgkmcnt(7)
	ds_read_b128 v[152:155], v215 offset:4672
	s_waitcnt lgkmcnt(7)
	ds_read_b128 v[156:159], v215 offset:4704
	s_setprio 1
	s_setprio 0
	v_add_f32_e32 v216, 0x41000000, v214
	s_cbranch_scc0 .LBB0_601
	s_waitcnt lgkmcnt(7)
	v_mfma_f32_32x32x16_bf16 v[32:47], v[140:143], v[96:99], 0
	s_waitcnt lgkmcnt(6)
	v_mfma_f32_32x32x16_bf16 v[32:47], v[136:139], v[100:103], v[32:47]
	s_waitcnt lgkmcnt(5)
	v_mfma_f32_32x32x16_bf16 v[32:47], v[132:135], v[104:107], v[32:47]
	s_waitcnt lgkmcnt(4)
	v_mfma_f32_32x32x16_bf16 v[32:47], v[128:131], v[108:111], v[32:47]
	s_waitcnt lgkmcnt(3)
	v_mfma_f32_32x32x16_bf16 v[64:79], v[144:147], v[96:99], 0
	s_nop 9
	v_max3_f32 v48, v32, s15, v33
	v_max3_f32 v48, v48, v34, v35
	v_max3_f32 v48, v48, v36, v37
	v_max3_f32 v48, v48, v38, v39
	v_max3_f32 v48, v48, v40, v41
	v_max3_f32 v48, v48, v42, v43
	v_max3_f32 v48, v48, v44, v45
	v_max3_f32 v48, v48, v46, v47
	v_cndmask_b32_e64 v48, v208, v48, s[38:39]
	v_mov_b32_e32 v49, v48
	v_mov_b32_e32 v50, v48
	s_nop 1
	v_permlane32_swap_b32_e32 v49, v50
	v_cndmask_b32_e64 v49, v49, v50, s[36:37]
	v_max_f32_e32 v49, v49, v49
	v_max_f32_e32 v48, v48, v49
	v_cmp_gt_f32_e32 vcc, v48, v216
	s_waitcnt lgkmcnt(2)
	v_mfma_f32_32x32x16_bf16 v[64:79], v[148:151], v[100:103], v[64:79]
	v_cndmask_b32_e32 v224, v214, v48, vcc
	v_max_f32_e32 v48, v224, v224
	v_max_f32_e32 v48, 0xefa18f08, v48
	v_cndmask_b32_e64 v48, v209, v48, s[38:39]
	v_sub_f32_e32 v32, v32, v48
	v_sub_f32_e32 v33, v33, v48
	v_exp_f32_e32 v80, v32
	v_sub_f32_e32 v34, v34, v48
	v_exp_f32_e32 v81, v33
	v_sub_f32_e32 v35, v35, v48
	v_exp_f32_e32 v82, v34
	v_sub_f32_e32 v36, v36, v48
	v_exp_f32_e32 v83, v35
	v_sub_f32_e32 v37, v37, v48
	v_exp_f32_e32 v84, v36
	v_add_f32_e32 v32, 0, v80
	v_sub_f32_e32 v38, v38, v48
	v_exp_f32_e32 v85, v37
	v_add_f32_e32 v32, v81, v32
	v_sub_f32_e32 v39, v39, v48
	v_exp_f32_e32 v86, v38
	s_waitcnt lgkmcnt(1)
	v_mfma_f32_32x32x16_bf16 v[64:79], v[152:155], v[104:107], v[64:79]
	v_add_f32_e32 v32, v82, v32
	v_sub_f32_e32 v40, v40, v48
	v_exp_f32_e32 v87, v39
	v_add_f32_e32 v32, v83, v32
	v_sub_f32_e32 v41, v41, v48
	v_exp_f32_e32 v88, v40
	v_add_f32_e32 v32, v84, v32
	v_sub_f32_e32 v42, v42, v48
	v_exp_f32_e32 v89, v41
	v_add_f32_e32 v32, v85, v32
	v_sub_f32_e32 v43, v43, v48
	v_exp_f32_e32 v90, v42
	v_add_f32_e32 v32, v86, v32
	v_sub_f32_e32 v44, v44, v48
	v_exp_f32_e32 v91, v43
	v_add_f32_e32 v32, v87, v32
	v_add_f32_e32 v32, v88, v32
	v_exp_f32_e32 v92, v44
	v_sub_f32_e32 v33, v45, v48
	v_add_f32_e32 v32, v89, v32
	v_exp_f32_e32 v93, v33
	v_sub_f32_e32 v33, v46, v48
	s_waitcnt lgkmcnt(0)
	v_mfma_f32_32x32x16_bf16 v[64:79], v[156:159], v[108:111], v[64:79]
	v_add_f32_e32 v32, v90, v32
	v_exp_f32_e32 v94, v33
	v_sub_f32_e32 v33, v47, v48
	v_add_f32_e32 v32, v91, v32
	v_exp_f32_e32 v95, v33
	v_add_f32_e32 v32, v92, v32
	v_sub_f32_e32 v49, v214, v224
	v_add_f32_e32 v32, v93, v32
	v_add_f32_e32 v32, v94, v32
	v_exp_f32_e32 v166, v49
	v_add_f32_e32 v217, v95, v32
	v_mov_b32_e32 v218, v217
	v_mov_b32_e32 v219, v217
	s_nop 0
	s_nop 0
	v_permlane32_swap_b32_e32 v218, v219
	v_cmp_neq_f32_e32 vcc, v224, v214
	s_cbranch_vccz .LBB0_594
	v_pk_mul_f32 v[30:31], v[30:31], v[166:167] op_sel_hi:[1,0]
	v_pk_mul_f32 v[28:29], v[28:29], v[166:167] op_sel_hi:[1,0]
	v_pk_mul_f32 v[26:27], v[26:27], v[166:167] op_sel_hi:[1,0]
	v_pk_mul_f32 v[24:25], v[24:25], v[166:167] op_sel_hi:[1,0]
	v_pk_mul_f32 v[22:23], v[22:23], v[166:167] op_sel_hi:[1,0]
	v_pk_mul_f32 v[20:21], v[20:21], v[166:167] op_sel_hi:[1,0]
	v_pk_mul_f32 v[18:19], v[18:19], v[166:167] op_sel_hi:[1,0]
	v_pk_mul_f32 v[16:17], v[16:17], v[166:167] op_sel_hi:[1,0]
	v_pk_mul_f32 v[14:15], v[14:15], v[166:167] op_sel_hi:[1,0]
	v_pk_mul_f32 v[12:13], v[12:13], v[166:167] op_sel_hi:[1,0]
	v_pk_mul_f32 v[10:11], v[10:11], v[166:167] op_sel_hi:[1,0]
	v_pk_mul_f32 v[8:9], v[8:9], v[166:167] op_sel_hi:[1,0]
	v_pk_mul_f32 v[6:7], v[6:7], v[166:167] op_sel_hi:[1,0]
	v_pk_mul_f32 v[4:5], v[4:5], v[166:167] op_sel_hi:[1,0]
	v_pk_mul_f32 v[2:3], v[2:3], v[166:167] op_sel_hi:[1,0]
	v_pk_mul_f32 v[0:1], v[0:1], v[166:167] op_sel_hi:[1,0]
; #define LAS __attribute__((address_space(3)))
; DI float ex2(float x) { return __builtin_amdgcn_exp2f(x); }
; template <int MM> DI void smax_step_nb(const f32x16& s, unsigned vm, float& m, float& l, f32x16 (&o)[2], bf16x8 (&pf)[2], int lane) {
;     float mx = -1e30f;
; #pragma unroll
;     for (int i = 0; i < 16; ++i) mx = fmaxf(mx, s[i]);
;     if (MM == 1) mx = vm ? mx : -1e30f;
;     mx = fmaxf(mx, shx32(mx, lane));
;     const float mn = (mx > m + 8.0f) ? mx : m;
;     float mref = fmaxf(mn, -1e29f);
;     if (MM == 1) mref = vm ? mref : 3e38f;
;     const float alpha = ex2(m - mn);
;     float p[16], rs = 0.f;
; #pragma unroll
;     for (int i = 0; i < 16; ++i) { p[i] = ex2(s[i] - mref); rs += p[i]; }
;     rs += shx32(rs, lane);
;     l = l * alpha + rs;
;     if (__builtin_amdgcn_ballot_w64(mn != m) != 0ull) {
; #pragma unroll
;         for (int i = 0; i < 16; ++i) { o[0][i] *= alpha; o[1][i] *= alpha; }
;     }
;     m = mn;
;     pack_p(p, pf);
; }
; template <int MM> DI void tile128_pipe(LAS const char* K0, LAS const char* V0, LAS const char* K1, LAS const char* V1, const bf16x8 (&qf)[4], unsigned vm0, unsigned vm1,
;                                        float& m, float& l, f32x16 (&o)[2], int r, int h, int lane) {
;     f32x16 sa = qk_rows<0, 4>(K0, 0, qf, r, h), sb = qk_rows<0, 4>(K0, 32, qf, r, h);
;     bf16x8 pfa[2], pfb[2];
;     smax_step_nb<MM>(sa, vm0, m, l, o, pfa, lane);
;     sa = qk_rows<0, 4>(K1, 0, qf, r, h);
;     pv_rows(o, V0, 0, pfa, lane);
;     smax_step_nb<MM>(sb, vm0, m, l, o, pfb, lane);
;     sb = qk_rows<0, 4>(K1, 32, qf, r, h);
;     pv_rows(o, V0, 32, pfb, lane);
;     smax_step_nb<MM>(sa, vm1, m, l, o, pfa, lane);
;     pv_rows(o, V1, 0, pfa, lane);
;     smax_step_nb<MM>(sb, vm1, m, l, o, pfb, lane);
;     pv_rows(o, V1, 32, pfb, lane);
; }
.LBB0_594:
	v_cvt_pk_bf16_f32 v226, v80, v81
	v_cvt_pk_bf16_f32 v227, v82, v83
	ds_read_b128 v[80:83], v215 offset:18432
	ds_read_b128 v[220:223], v215 offset:18464
	ds_read_b128 v[234:237], v215 offset:18496
	ds_read_b128 v[238:241], v215 offset:18528
	v_cvt_pk_bf16_f32 v228, v84, v85
	v_cvt_pk_bf16_f32 v229, v86, v87
	v_cvt_pk_bf16_f32 v230, v88, v89
	v_cvt_pk_bf16_f32 v231, v90, v91
	v_cvt_pk_bf16_f32 v232, v92, v93
	v_cvt_pk_bf16_f32 v233, v94, v95
	s_setprio 1
	s_waitcnt lgkmcnt(3)
	v_mfma_f32_32x32x16_bf16 v[80:95], v[80:83], v[96:99], 0
	s_waitcnt lgkmcnt(2)
	v_mfma_f32_32x32x16_bf16 v[80:95], v[220:223], v[100:103], v[80:95]
	s_waitcnt lgkmcnt(1)
	v_mfma_f32_32x32x16_bf16 v[80:95], v[234:237], v[104:107], v[80:95]
	s_waitcnt lgkmcnt(0)
	v_mfma_f32_32x32x16_bf16 v[80:95], v[238:241], v[108:111], v[80:95]
	s_setprio 0
	v_add3_u32 v172, s10, v191, v171
	v_add_u32_e32 v220, v172, v186
	ds_read_b64_tr_b16 v[234:235], v220 offset:9216
	ds_read_b64_tr_b16 v[236:237], v220 offset:10368
	ds_read_b64_tr_b16 v[240:241], v220 offset:10432
	ds_read_b64_tr_b16 v[238:239], v220 offset:9280
	ds_read_b64_tr_b16 v[242:243], v220 offset:11520
	ds_read_b64_tr_b16 v[244:245], v220 offset:12672
	ds_read_b64_tr_b16 v[248:249], v220 offset:12736
	ds_read_b64_tr_b16 v[246:247], v220 offset:11584
	s_setprio 1
	s_waitcnt lgkmcnt(6)
	v_mfma_f32_32x32x16_bf16 v[0:15], v[234:237], v[226:229], v[0:15]
	s_waitcnt lgkmcnt(4)
	v_mfma_f32_32x32x16_bf16 v[16:31], v[238:241], v[226:229], v[16:31]
	s_waitcnt lgkmcnt(2)
	v_mfma_f32_32x32x16_bf16 v[0:15], v[242:245], v[230:233], v[0:15]
	s_waitcnt lgkmcnt(0)
	v_mfma_f32_32x32x16_bf16 v[16:31], v[246:249], v[230:233], v[16:31]
	s_setprio 0
	v_max3_f32 v172, v64, s15, v65
	v_max3_f32 v172, v172, v66, v67
	v_max3_f32 v172, v172, v68, v69
	v_max3_f32 v172, v172, v70, v71
	v_max3_f32 v172, v172, v72, v73
	v_max3_f32 v172, v172, v74, v75
	v_max3_f32 v172, v172, v76, v77
	v_max3_f32 v172, v172, v78, v79
	v_cndmask_b32_e64 v172, v208, v172, s[38:39]
	v_mov_b32_e32 v173, v172
	v_mov_b32_e32 v184, v172
	s_nop 1
	v_permlane32_swap_b32_e32 v173, v184
	v_cndmask_b32_e64 v173, v173, v184, s[36:37]
	v_max_f32_e32 v173, v173, v173
	v_max_f32_e32 v172, v172, v173
	v_add_f32_e32 v173, 0x41000000, v224
	v_cmp_gt_f32_e32 vcc, v172, v173
	s_nop 1
	v_cndmask_b32_e32 v225, v224, v172, vcc
	v_max_f32_e32 v172, v225, v225
	v_max_f32_e32 v172, 0xefa18f08, v172
	v_cndmask_b32_e64 v172, v209, v172, s[38:39]
	v_sub_f32_e32 v64, v64, v172
	v_exp_f32_e32 v64, v64
	v_sub_f32_e32 v65, v65, v172
	v_exp_f32_e32 v65, v65
	v_sub_f32_e32 v66, v66, v172
	v_exp_f32_e32 v66, v66
	v_sub_f32_e32 v67, v67, v172
	v_exp_f32_e32 v67, v67
	v_sub_f32_e32 v68, v68, v172
	v_add_f32_e32 v184, 0, v64
	v_exp_f32_e32 v68, v68
	v_sub_f32_e32 v69, v69, v172
	v_add_f32_e32 v184, v65, v184
	v_exp_f32_e32 v69, v69
	v_sub_f32_e32 v70, v70, v172
	v_add_f32_e32 v184, v66, v184
	v_exp_f32_e32 v70, v70
	v_sub_f32_e32 v71, v71, v172
	v_add_f32_e32 v184, v67, v184
	v_exp_f32_e32 v71, v71
	v_sub_f32_e32 v72, v72, v172
	v_add_f32_e32 v184, v68, v184
	v_exp_f32_e32 v72, v72
	v_sub_f32_e32 v73, v73, v172
	v_add_f32_e32 v184, v69, v184
	v_exp_f32_e32 v73, v73
	v_sub_f32_e32 v74, v74, v172
	v_add_f32_e32 v184, v70, v184
	v_exp_f32_e32 v74, v74
	v_sub_f32_e32 v75, v75, v172
	v_add_f32_e32 v184, v71, v184
	v_exp_f32_e32 v75, v75
	v_sub_f32_e32 v76, v76, v172
	v_add_f32_e32 v184, v72, v184
	v_exp_f32_e32 v76, v76
	v_sub_f32_e32 v77, v77, v172
	v_add_f32_e32 v184, v73, v184
	v_exp_f32_e32 v77, v77
	v_sub_f32_e32 v78, v78, v172
	v_add_f32_e32 v184, v74, v184
	v_exp_f32_e32 v78, v78
	v_sub_f32_e32 v79, v79, v172
	v_add_f32_e32 v184, v75, v184
	v_exp_f32_e32 v79, v79
	v_add_f32_e32 v172, v76, v184
	v_sub_f32_e32 v173, v224, v225
	v_add_f32_e32 v172, v77, v172
	v_add_f32_e32 v172, v78, v172
	v_exp_f32_e32 v184, v173
	v_add_f32_e32 v221, v79, v172
	v_mov_b32_e32 v222, v221
	v_mov_b32_e32 v223, v221
	s_nop 1
	v_permlane32_swap_b32_e32 v222, v223
	v_cmp_neq_f32_e32 vcc, v225, v224
	s_cbranch_vccz .LBB0_596
	v_pk_mul_f32 v[30:31], v[30:31], v[184:185] op_sel_hi:[1,0]
	v_pk_mul_f32 v[28:29], v[28:29], v[184:185] op_sel_hi:[1,0]
	v_pk_mul_f32 v[26:27], v[26:27], v[184:185] op_sel_hi:[1,0]
	v_pk_mul_f32 v[24:25], v[24:25], v[184:185] op_sel_hi:[1,0]
	v_pk_mul_f32 v[22:23], v[22:23], v[184:185] op_sel_hi:[1,0]
	v_pk_mul_f32 v[20:21], v[20:21], v[184:185] op_sel_hi:[1,0]
	v_pk_mul_f32 v[18:19], v[18:19], v[184:185] op_sel_hi:[1,0]
	v_pk_mul_f32 v[16:17], v[16:17], v[184:185] op_sel_hi:[1,0]
	v_pk_mul_f32 v[14:15], v[14:15], v[184:185] op_sel_hi:[1,0]
	v_pk_mul_f32 v[12:13], v[12:13], v[184:185] op_sel_hi:[1,0]
	v_pk_mul_f32 v[10:11], v[10:11], v[184:185] op_sel_hi:[1,0]
	v_pk_mul_f32 v[8:9], v[8:9], v[184:185] op_sel_hi:[1,0]
	v_pk_mul_f32 v[6:7], v[6:7], v[184:185] op_sel_hi:[1,0]
	v_pk_mul_f32 v[4:5], v[4:5], v[184:185] op_sel_hi:[1,0]
	v_pk_mul_f32 v[2:3], v[2:3], v[184:185] op_sel_hi:[1,0]
	v_pk_mul_f32 v[0:1], v[0:1], v[184:185] op_sel_hi:[1,0]
; #define LAS __attribute__((address_space(3)))
; DI float ex2(float x) { return __builtin_amdgcn_exp2f(x); }
; template <int MM> DI void smax_step_nb(const f32x16& s, unsigned vm, float& m, float& l, f32x16 (&o)[2], bf16x8 (&pf)[2], int lane) {
;     float mx = -1e30f;
; #pragma unroll
;     for (int i = 0; i < 16; ++i) mx = fmaxf(mx, s[i]);
;     if (MM == 1) mx = vm ? mx : -1e30f;
;     mx = fmaxf(mx, shx32(mx, lane));
;     const float mn = (mx > m + 8.0f) ? mx : m;
;     float mref = fmaxf(mn, -1e29f);
;     if (MM == 1) mref = vm ? mref : 3e38f;
;     const float alpha = ex2(m - mn);
;     float p[16], rs = 0.f;
; #pragma unroll
;     for (int i = 0; i < 16; ++i) { p[i] = ex2(s[i] - mref); rs += p[i]; }
;     rs += shx32(rs, lane);
;     l = l * alpha + rs;
;     if (__builtin_amdgcn_ballot_w64(mn != m) != 0ull) {
; #pragma unroll
;         for (int i = 0; i < 16; ++i) { o[0][i] *= alpha; o[1][i] *= alpha; }
;     }
;     m = mn;
;     pack_p(p, pf);
; }
; template <int MM> DI void tile128_pipe(LAS const char* K0, LAS const char* V0, LAS const char* K1, LAS const char* V1, const bf16x8 (&qf)[4], unsigned vm0, unsigned vm1,
;                                        float& m, float& l, f32x16 (&o)[2], int r, int h, int lane) {
;     f32x16 sa = qk_rows<0, 4>(K0, 0, qf, r, h), sb = qk_rows<0, 4>(K0, 32, qf, r, h);
;     bf16x8 pfa[2], pfb[2];
;     smax_step_nb<MM>(sa, vm0, m, l, o, pfa, lane);
;     sa = qk_rows<0, 4>(K1, 0, qf, r, h);
;     pv_rows(o, V0, 0, pfa, lane);
;     smax_step_nb<MM>(sb, vm0, m, l, o, pfb, lane);
;     sb = qk_rows<0, 4>(K1, 32, qf, r, h);
;     pv_rows(o, V0, 32, pfb, lane);
;     smax_step_nb<MM>(sa, vm1, m, l, o, pfa, lane);
;     pv_rows(o, V1, 0, pfa, lane);
;     smax_step_nb<MM>(sb, vm1, m, l, o, pfb, lane);
;     pv_rows(o, V1, 32, pfb, lane);
; }
.LBB0_596:
	v_cvt_pk_bf16_f32 v226, v64, v65
	v_cvt_pk_bf16_f32 v227, v66, v67
	ds_read_b128 v[64:67], v215 offset:23040
	ds_read_b128 v[234:237], v215 offset:23072
	ds_read_b128 v[238:241], v215 offset:23104
	ds_read_b128 v[242:245], v215 offset:23136
	v_cvt_pk_bf16_f32 v228, v68, v69
	v_cvt_pk_bf16_f32 v229, v70, v71
	v_cvt_pk_bf16_f32 v230, v72, v73
	v_cvt_pk_bf16_f32 v231, v74, v75
	v_cvt_pk_bf16_f32 v232, v76, v77
	v_cvt_pk_bf16_f32 v233, v78, v79
	s_setprio 1
	s_waitcnt lgkmcnt(3)
	v_mfma_f32_32x32x16_bf16 v[64:79], v[64:67], v[96:99], 0
	s_waitcnt lgkmcnt(2)
	v_mfma_f32_32x32x16_bf16 v[64:79], v[234:237], v[100:103], v[64:79]
	s_waitcnt lgkmcnt(1)
	v_mfma_f32_32x32x16_bf16 v[64:79], v[238:241], v[104:107], v[64:79]
	s_waitcnt lgkmcnt(0)
	v_mfma_f32_32x32x16_bf16 v[64:79], v[242:245], v[108:111], v[64:79]
	s_setprio 0
	ds_read_b64_tr_b16 v[234:235], v220 offset:13824
	ds_read_b64_tr_b16 v[236:237], v220 offset:14976
	ds_read_b64_tr_b16 v[240:241], v220 offset:15040
	ds_read_b64_tr_b16 v[238:239], v220 offset:13888
	ds_read_b64_tr_b16 v[242:243], v220 offset:16128
	ds_read_b64_tr_b16 v[244:245], v220 offset:17280
	ds_read_b64_tr_b16 v[248:249], v220 offset:17344
	ds_read_b64_tr_b16 v[246:247], v220 offset:16192
	s_setprio 1
	s_waitcnt lgkmcnt(6)
	v_mfma_f32_32x32x16_bf16 v[0:15], v[234:237], v[226:229], v[0:15]
	s_waitcnt lgkmcnt(4)
	v_mfma_f32_32x32x16_bf16 v[16:31], v[238:241], v[226:229], v[16:31]
	s_waitcnt lgkmcnt(2)
	v_mfma_f32_32x32x16_bf16 v[0:15], v[242:245], v[230:233], v[0:15]
	s_waitcnt lgkmcnt(0)
	v_mfma_f32_32x32x16_bf16 v[16:31], v[246:249], v[230:233], v[16:31]
	s_setprio 0
	v_max3_f32 v172, v80, s15, v81
	v_max3_f32 v172, v172, v82, v83
	v_max3_f32 v172, v172, v84, v85
	v_max3_f32 v172, v172, v86, v87
	v_max3_f32 v172, v172, v88, v89
	v_max3_f32 v172, v172, v90, v91
	v_max3_f32 v172, v172, v92, v93
	v_max3_f32 v172, v172, v94, v95
	v_cndmask_b32_e64 v172, v208, v172, s[0:1]
	v_mov_b32_e32 v173, v172
	v_mov_b32_e32 v206, v172
	s_nop 1
	v_permlane32_swap_b32_e32 v173, v206
	v_cndmask_b32_e64 v173, v173, v206, s[36:37]
	v_max_f32_e32 v173, v173, v173
	v_max_f32_e32 v172, v172, v173
	v_add_f32_e32 v173, 0x41000000, v225
	v_cmp_gt_f32_e32 vcc, v172, v173
	s_nop 1
	v_cndmask_b32_e32 v224, v225, v172, vcc
	v_max_f32_e32 v172, v224, v224
	v_max_f32_e32 v172, 0xefa18f08, v172
	v_cndmask_b32_e64 v172, v209, v172, s[0:1]
	v_sub_f32_e32 v80, v80, v172
	v_exp_f32_e32 v226, v80
	v_sub_f32_e32 v80, v81, v172
	v_exp_f32_e32 v81, v80
	v_sub_f32_e32 v80, v82, v172
	v_exp_f32_e32 v227, v80
	v_sub_f32_e32 v80, v83, v172
	v_exp_f32_e32 v228, v80
	v_sub_f32_e32 v82, v84, v172
	v_add_f32_e32 v80, 0, v226
	v_exp_f32_e32 v229, v82
	v_sub_f32_e32 v82, v85, v172
	v_add_f32_e32 v80, v81, v80
	v_exp_f32_e32 v85, v82
	v_sub_f32_e32 v82, v86, v172
	v_add_f32_e32 v80, v227, v80
	v_exp_f32_e32 v86, v82
	v_sub_f32_e32 v82, v87, v172
	v_add_f32_e32 v80, v228, v80
	v_exp_f32_e32 v87, v82
	v_sub_f32_e32 v82, v88, v172
	v_add_f32_e32 v80, v229, v80
	v_exp_f32_e32 v88, v82
	v_sub_f32_e32 v82, v89, v172
	v_add_f32_e32 v80, v85, v80
	v_exp_f32_e32 v89, v82
	v_sub_f32_e32 v82, v90, v172
	v_add_f32_e32 v80, v86, v80
	v_exp_f32_e32 v90, v82
	v_sub_f32_e32 v82, v91, v172
	v_add_f32_e32 v80, v87, v80
	v_exp_f32_e32 v91, v82
	v_sub_f32_e32 v82, v92, v172
	v_add_f32_e32 v80, v88, v80
	v_exp_f32_e32 v92, v82
	v_sub_f32_e32 v82, v93, v172
	v_add_f32_e32 v80, v89, v80
	v_exp_f32_e32 v93, v82
	v_sub_f32_e32 v82, v94, v172
	v_add_f32_e32 v80, v90, v80
	v_exp_f32_e32 v94, v82
	v_sub_f32_e32 v82, v95, v172
	v_add_f32_e32 v80, v91, v80
	v_exp_f32_e32 v95, v82
	v_add_f32_e32 v80, v92, v80
	v_add_f32_e32 v80, v93, v80
	v_sub_f32_e32 v173, v225, v224
	v_add_f32_e32 v80, v94, v80
	v_add_f32_e32 v82, v95, v80
	v_exp_f32_e32 v80, v173
	v_mov_b32_e32 v83, v82
	v_mov_b32_e32 v84, v82
	s_nop 1
	v_permlane32_swap_b32_e32 v83, v84
	v_cmp_neq_f32_e32 vcc, v224, v225
	s_cbranch_vccz .LBB0_598
	v_pk_mul_f32 v[30:31], v[30:31], v[80:81] op_sel_hi:[1,0]
	v_pk_mul_f32 v[28:29], v[28:29], v[80:81] op_sel_hi:[1,0]
	v_pk_mul_f32 v[26:27], v[26:27], v[80:81] op_sel_hi:[1,0]
	v_pk_mul_f32 v[24:25], v[24:25], v[80:81] op_sel_hi:[1,0]
	v_pk_mul_f32 v[22:23], v[22:23], v[80:81] op_sel_hi:[1,0]
	v_pk_mul_f32 v[20:21], v[20:21], v[80:81] op_sel_hi:[1,0]
	v_pk_mul_f32 v[18:19], v[18:19], v[80:81] op_sel_hi:[1,0]
	v_pk_mul_f32 v[16:17], v[16:17], v[80:81] op_sel_hi:[1,0]
	v_pk_mul_f32 v[14:15], v[14:15], v[80:81] op_sel_hi:[1,0]
	v_pk_mul_f32 v[12:13], v[12:13], v[80:81] op_sel_hi:[1,0]
	v_pk_mul_f32 v[10:11], v[10:11], v[80:81] op_sel_hi:[1,0]
	v_pk_mul_f32 v[8:9], v[8:9], v[80:81] op_sel_hi:[1,0]
	v_pk_mul_f32 v[6:7], v[6:7], v[80:81] op_sel_hi:[1,0]
	v_pk_mul_f32 v[4:5], v[4:5], v[80:81] op_sel_hi:[1,0]
	v_pk_mul_f32 v[2:3], v[2:3], v[80:81] op_sel_hi:[1,0]
	v_pk_mul_f32 v[0:1], v[0:1], v[80:81] op_sel_hi:[1,0]
; #define LAS __attribute__((address_space(3)))
; DI float ex2(float x) { return __builtin_amdgcn_exp2f(x); }
; template <int MM> DI void smax_step_nb(const f32x16& s, unsigned vm, float& m, float& l, f32x16 (&o)[2], bf16x8 (&pf)[2], int lane) {
;     float mx = -1e30f;
; #pragma unroll
;     for (int i = 0; i < 16; ++i) mx = fmaxf(mx, s[i]);
;     if (MM == 1) mx = vm ? mx : -1e30f;
;     mx = fmaxf(mx, shx32(mx, lane));
;     const float mn = (mx > m + 8.0f) ? mx : m;
;     float mref = fmaxf(mn, -1e29f);
;     if (MM == 1) mref = vm ? mref : 3e38f;
;     const float alpha = ex2(m - mn);
;     float p[16], rs = 0.f;
; #pragma unroll
;     for (int i = 0; i < 16; ++i) { p[i] = ex2(s[i] - mref); rs += p[i]; }
;     rs += shx32(rs, lane);
;     l = l * alpha + rs;
;     if (__builtin_amdgcn_ballot_w64(mn != m) != 0ull) {
; #pragma unroll
;         for (int i = 0; i < 16; ++i) { o[0][i] *= alpha; o[1][i] *= alpha; }
;     }
;     m = mn;
;     pack_p(p, pf);
; }
; template <int MM> DI void tile128_pipe(LAS const char* K0, LAS const char* V0, LAS const char* K1, LAS const char* V1, const bf16x8 (&qf)[4], unsigned vm0, unsigned vm1,
;                                        float& m, float& l, f32x16 (&o)[2], int r, int h, int lane) {
;     f32x16 sa = qk_rows<0, 4>(K0, 0, qf, r, h), sb = qk_rows<0, 4>(K0, 32, qf, r, h);
;     bf16x8 pfa[2], pfb[2];
;     smax_step_nb<MM>(sa, vm0, m, l, o, pfa, lane);
;     sa = qk_rows<0, 4>(K1, 0, qf, r, h);
;     pv_rows(o, V0, 0, pfa, lane);
;     smax_step_nb<MM>(sb, vm0, m, l, o, pfb, lane);
;     sb = qk_rows<0, 4>(K1, 32, qf, r, h);
;     pv_rows(o, V0, 32, pfb, lane);
;     smax_step_nb<MM>(sa, vm1, m, l, o, pfa, lane);
;     pv_rows(o, V1, 0, pfa, lane);
;     smax_step_nb<MM>(sb, vm1, m, l, o, pfb, lane);
;     pv_rows(o, V1, 32, pfb, lane);
; }
.LBB0_598:
	v_cvt_pk_bf16_f32 v227, v227, v228
	v_cvt_pk_bf16_f32 v228, v229, v85
	v_cvt_pk_bf16_f32 v229, v86, v87
	v_cvt_pk_bf16_f32 v86, v88, v89
	v_cvt_pk_bf16_f32 v87, v90, v91
	v_cvt_pk_bf16_f32 v88, v92, v93
	ds_read_b64_tr_b16 v[90:91], v220 offset:27648
	ds_read_b64_tr_b16 v[92:93], v220 offset:28800
	ds_read_b64_tr_b16 v[230:231], v220 offset:29952
	ds_read_b64_tr_b16 v[232:233], v220 offset:31104
	ds_read_b64_tr_b16 v[234:235], v220 offset:27712
	ds_read_b64_tr_b16 v[236:237], v220 offset:28864
	ds_read_b64_tr_b16 v[238:239], v220 offset:30016
	ds_read_b64_tr_b16 v[240:241], v220 offset:31168
	v_cvt_pk_bf16_f32 v89, v94, v95
	v_cvt_pk_bf16_f32 v226, v226, v81
	s_setprio 1
	s_waitcnt lgkmcnt(6)
	v_mfma_f32_32x32x16_bf16 v[0:15], v[90:93], v[226:229], v[0:15]
	s_waitcnt lgkmcnt(2)
	v_mfma_f32_32x32x16_bf16 v[16:31], v[234:237], v[226:229], v[16:31]
	v_mfma_f32_32x32x16_bf16 v[0:15], v[230:233], v[86:89], v[0:15]
	s_waitcnt lgkmcnt(0)
	v_mfma_f32_32x32x16_bf16 v[16:31], v[238:241], v[86:89], v[16:31]
	s_setprio 0
	v_max3_f32 v81, v64, s15, v65
	v_max3_f32 v81, v81, v66, v67
	v_max3_f32 v81, v81, v68, v69
	v_max3_f32 v81, v81, v70, v71
	v_max3_f32 v81, v81, v72, v73
	v_max3_f32 v81, v81, v74, v75
	v_max3_f32 v81, v81, v76, v77
	v_max3_f32 v81, v81, v78, v79
	v_cndmask_b32_e64 v81, v208, v81, s[0:1]
	v_mov_b32_e32 v85, v81
	v_mov_b32_e32 v86, v81
	s_nop 1
	v_permlane32_swap_b32_e32 v85, v86
	v_cndmask_b32_e64 v85, v85, v86, s[36:37]
	v_max_f32_e32 v85, v85, v85
	v_max_f32_e32 v81, v81, v85
	v_add_f32_e32 v85, 0x41000000, v224
	v_cmp_gt_f32_e32 vcc, v81, v85
	s_nop 1
	v_cndmask_b32_e32 v81, v224, v81, vcc
	v_max_f32_e32 v85, v81, v81
	v_max_f32_e32 v85, 0xefa18f08, v85
	v_cndmask_b32_e64 v93, v209, v85, s[0:1]
	v_sub_f32_e32 v64, v64, v93
	v_exp_f32_e32 v85, v64
	v_sub_f32_e32 v64, v65, v93
	v_exp_f32_e32 v86, v64
	v_sub_f32_e32 v64, v66, v93
	v_exp_f32_e32 v87, v64
	v_sub_f32_e32 v64, v67, v93
	v_exp_f32_e32 v88, v64
	v_sub_f32_e32 v65, v68, v93
	v_add_f32_e32 v64, 0, v85
	v_exp_f32_e32 v89, v65
	v_sub_f32_e32 v65, v69, v93
	v_add_f32_e32 v64, v86, v64
	v_exp_f32_e32 v90, v65
	v_sub_f32_e32 v65, v70, v93
	v_add_f32_e32 v64, v87, v64
	v_exp_f32_e32 v91, v65
	v_sub_f32_e32 v65, v71, v93
	v_add_f32_e32 v64, v88, v64
	v_exp_f32_e32 v92, v65
	v_sub_f32_e32 v65, v72, v93
	v_add_f32_e32 v64, v89, v64
	v_exp_f32_e32 v66, v65
	v_sub_f32_e32 v65, v73, v93
	v_add_f32_e32 v64, v90, v64
	v_exp_f32_e32 v67, v65
	v_sub_f32_e32 v65, v74, v93
	v_add_f32_e32 v64, v91, v64
	v_exp_f32_e32 v68, v65
	v_sub_f32_e32 v65, v75, v93
	v_add_f32_e32 v64, v92, v64
	v_exp_f32_e32 v69, v65
	v_sub_f32_e32 v65, v76, v93
	v_add_f32_e32 v64, v66, v64
	v_exp_f32_e32 v70, v65
	v_sub_f32_e32 v65, v77, v93
	v_add_f32_e32 v64, v67, v64
	v_exp_f32_e32 v71, v65
	v_sub_f32_e32 v65, v78, v93
	v_add_f32_e32 v64, v68, v64
	v_exp_f32_e32 v72, v65
	v_sub_f32_e32 v65, v79, v93
	v_add_f32_e32 v64, v69, v64
	v_exp_f32_e32 v73, v65
	v_add_f32_e32 v64, v70, v64
	v_add_f32_e32 v64, v71, v64
	v_sub_f32_e32 v94, v224, v81
	v_add_f32_e32 v64, v72, v64
	v_add_f32_e32 v65, v73, v64
	v_exp_f32_e32 v64, v94
	v_mov_b32_e32 v74, v65
	v_mov_b32_e32 v75, v65
	s_nop 1
	v_permlane32_swap_b32_e32 v74, v75
	v_cmp_neq_f32_e32 vcc, v81, v224
	s_cbranch_vccz .LBB0_600
	v_pk_mul_f32 v[30:31], v[30:31], v[64:65] op_sel_hi:[1,0]
	v_pk_mul_f32 v[28:29], v[28:29], v[64:65] op_sel_hi:[1,0]
	v_pk_mul_f32 v[26:27], v[26:27], v[64:65] op_sel_hi:[1,0]
	v_pk_mul_f32 v[24:25], v[24:25], v[64:65] op_sel_hi:[1,0]
	v_pk_mul_f32 v[22:23], v[22:23], v[64:65] op_sel_hi:[1,0]
	v_pk_mul_f32 v[20:21], v[20:21], v[64:65] op_sel_hi:[1,0]
	v_pk_mul_f32 v[18:19], v[18:19], v[64:65] op_sel_hi:[1,0]
	v_pk_mul_f32 v[16:17], v[16:17], v[64:65] op_sel_hi:[1,0]
	v_pk_mul_f32 v[14:15], v[14:15], v[64:65] op_sel_hi:[1,0]
	v_pk_mul_f32 v[12:13], v[12:13], v[64:65] op_sel_hi:[1,0]
	v_pk_mul_f32 v[10:11], v[10:11], v[64:65] op_sel_hi:[1,0]
	v_pk_mul_f32 v[8:9], v[8:9], v[64:65] op_sel_hi:[1,0]
	v_pk_mul_f32 v[6:7], v[6:7], v[64:65] op_sel_hi:[1,0]
	v_pk_mul_f32 v[4:5], v[4:5], v[64:65] op_sel_hi:[1,0]
	v_pk_mul_f32 v[2:3], v[2:3], v[64:65] op_sel_hi:[1,0]
	v_pk_mul_f32 v[0:1], v[0:1], v[64:65] op_sel_hi:[1,0]
.LBB0_600:
	v_cndmask_b32_e64 v76, v218, v219, s[36:37]
	v_add_f32_e32 v76, v217, v76
	v_cndmask_b32_e64 v77, v222, v223, s[36:37]
	v_fmac_f32_e32 v76, v213, v166
	v_add_f32_e32 v77, v221, v77
	v_fmac_f32_e32 v77, v76, v184
	v_cndmask_b32_e64 v76, v83, v84, s[36:37]
	v_add_f32_e32 v76, v82, v76
	v_cndmask_b32_e64 v74, v74, v75, s[36:37]
	v_fmac_f32_e32 v76, v77, v80
	v_add_f32_e32 v65, v65, v74
	v_fmac_f32_e32 v65, v76, v64
	v_cvt_pk_bf16_f32 v74, v85, v86
	v_cvt_pk_bf16_f32 v75, v87, v88
	v_cvt_pk_bf16_f32 v76, v89, v90
	v_cvt_pk_bf16_f32 v77, v91, v92
	ds_read_b64_tr_b16 v[84:85], v220 offset:33408
	ds_read_b64_tr_b16 v[86:87], v220 offset:34560
	ds_read_b64_tr_b16 v[90:91], v220 offset:34624
	ds_read_b64_tr_b16 v[224:225], v220 offset:33472
	ds_read_b64_tr_b16 v[82:83], v220 offset:32256
	ds_read_b64_tr_b16 v[88:89], v220 offset:35712
	ds_read_b64_tr_b16 v[222:223], v220 offset:32320
	ds_read_b64_tr_b16 v[92:93], v220 offset:35776
	v_cvt_pk_bf16_f32 v66, v66, v67
	v_cvt_pk_bf16_f32 v67, v68, v69
	v_cvt_pk_bf16_f32 v68, v70, v71
	v_cvt_pk_bf16_f32 v69, v72, v73
	s_setprio 1
	s_waitcnt lgkmcnt(3)
	v_mfma_f32_32x32x16_bf16 v[0:15], v[82:85], v[74:77], v[0:15]
	s_waitcnt lgkmcnt(1)
	v_mfma_f32_32x32x16_bf16 v[16:31], v[222:225], v[74:77], v[16:31]
	v_mfma_f32_32x32x16_bf16 v[0:15], v[86:89], v[66:69], v[0:15]
	s_waitcnt lgkmcnt(0)
	v_mfma_f32_32x32x16_bf16 v[16:31], v[90:93], v[66:69], v[16:31]
	s_branch .LBB0_611

; #define LAS __attribute__((address_space(3)))
; template <int MODE, bool PRE = false> ...
;     ...
;                 if (b0 != 0ull && b1 != 0ull) {
;                     LAS char* K0 = lds + (sti & 1) * 4 * TILE_B;
;                     if ((b0 & b1) == ~0ull) tile128_pipe<0>(K0, K0 + TILE_B, K0 + 2 * TILE_B, K0 + 3 * TILE_B, qf, 1u, 1u, m1, l1, o1, r, h, lane);
;                     else tile128_pipe<1>(K0, K0 + TILE_B, K0 + 2 * TILE_B, K0 + 3 * TILE_B, qf, ls0 ? 1u : 0u, ls1 ? 1u : 0u, m1, l1, o1, r, h, lane);
;                     goto step_done;
.LBB0_611:
	s_setprio 0
	s_mov_b32 s10, 9
	v_mov_b32_e32 v214, v81
	v_mov_b32_e32 v213, v65

; #define LAS __attribute__((address_space(3)))
; #define ST2_LOAD(T0) do { const int t0_ = (T0), t1_ = (t0_ + 1 > kt_hi) ? kt_hi : t0_ + 1; \
;         const size_t a0_ = (size_t)(64 * t0_ + skey) * pitch + 8 * sc, a1_ = (size_t)(64 * t1_ + skey) * pitch + 8 * sc; \
;         st.k0 = *(const u32x4*)(Kg + a0_); st.v0 = *(const u32x4*)(Vg + a0_); st.k1 = *(const u32x4*)(Kg + a1_); st.v1 = *(const u32x4*)(Vg + a1_); } while (0)
; template <int MM> DI void tile128_pipe(LAS const char* K0, LAS const char* V0, LAS const char* K1, LAS const char* V1, const bf16x8 (&qf)[4], unsigned vm0, unsigned vm1,
;                                        float& m, float& l, f32x16 (&o)[2], int r, int h, int lane) {
;     f32x16 sa = qk_rows<0, 4>(K0, 0, qf, r, h), sb = qk_rows<0, 4>(K0, 32, qf, r, h);
;     bf16x8 pfa[2], pfb[2];
;     smax_step_nb<MM>(sa, vm0, m, l, o, pfa, lane);
;     sa = qk_rows<0, 4>(K1, 0, qf, r, h);
; template <int MODE, bool PRE = false> ...
;     ...
;         if (sti + 1 < nst) ST2_LOAD(kt_lo + 2 * (sti + 1));
;         if (MODE != MODE_DIFF) {
;             const int kt0 = kt_lo + 2 * sti;
;             bool both = (kt0 + 1 <= kt_hi) && (64 * kt0 + 127 <= q0w);
;             if (MODE == MODE_NWIN) both = both && (64 * kt0 > q0w + 31 - 512);
;             if (both) {
;                 bool ls0 = true, ls1 = true;
;                 if (MODE == MODE_MOBA) { ls0 = ((sel >> (kt0 >> 2)) & 1ull) != 0ull; ls1 = ((sel >> ((kt0 + 1) >> 2)) & 1ull) != 0ull; }
;                 if (MODE == MODE_NSEL) { ls0 = ((sel >> kt0) & 1ull) != 0ull; ls1 = ((sel >> (kt0 + 1)) & 1ull) != 0ull; }
;                 const unsigned long long b0 = __builtin_amdgcn_ballot_w64(ls0), b1 = __builtin_amdgcn_ballot_w64(ls1);
;                 if (b0 != 0ull && b1 != 0ull) {
;                     LAS char* K0 = lds + (sti & 1) * 4 * TILE_B;
;                     if ((b0 & b1) == ~0ull) tile128_pipe<0>(K0, K0 + TILE_B, K0 + 2 * TILE_B, K0 + 3 * TILE_B, qf, 1u, 1u, m1, l1, o1, r, h, lane);
;                     else tile128_pipe<1>(K0, K0 + TILE_B, K0 + 2 * TILE_B, K0 + 3 * TILE_B, qf, ls0 ? 1u : 0u, ls1 ? 1u : 0u, m1, l1, o1, r, h, lane);
;                     goto step_done;
.LBB0_675:
	s_lshl_b32 s62, s44, 1
	s_add_i32 s62, s62, s27
	s_cmp_lt_u32 s62, s58
	s_cselect_b64 s[0:1], -1, 0
	s_lshl_b32 s24, s62, 6
	s_add_i32 s10, s24, 0x7f
	s_cmp_le_i32 s10, s59
	s_cselect_b64 s[10:11], -1, 0
	s_and_b64 s[0:1], s[0:1], s[10:11]
	s_cmp_gt_i32 s24, s57
	s_cselect_b64 s[10:11], -1, 0
	s_and_b64 s[0:1], s[0:1], s[10:11]
	s_andn2_b64 vcc, exec, s[0:1]
	s_mov_b32 s0, 0
	s_cbranch_vccnz .LBB0_698
	s_cmp_eq_u64 exec, 0
	s_cbranch_scc1 .LBB0_698
	s_lshl_b32 s0, s44, 2
	s_and_b32 s0, s0, 4
	s_mulk_i32 s0, 0x2400
	s_add_i32 s10, s0, 0
	v_add_u32_e32 v32, s10, v190
	v_add_u32_e32 v212, v32, v168
	s_waitcnt lgkmcnt(7)
	ds_read_b128 v[140:143], v212
	s_waitcnt lgkmcnt(7)
	ds_read_b128 v[136:139], v212 offset:32
	s_waitcnt lgkmcnt(7)
	ds_read_b128 v[132:135], v212 offset:64
	s_waitcnt lgkmcnt(7)
	ds_read_b128 v[128:131], v212 offset:96
	s_cmp_lg_u64 exec, -1
	s_setprio 1
	s_setprio 0
	s_waitcnt lgkmcnt(7)
	ds_read_b128 v[144:147], v212 offset:4608
	s_waitcnt lgkmcnt(7)
	ds_read_b128 v[148:151], v212 offset:4640
	s_waitcnt lgkmcnt(7)
	ds_read_b128 v[152:155], v212 offset:4672
	s_waitcnt lgkmcnt(7)
	ds_read_b128 v[156:159], v212 offset:4704
	s_setprio 1
	s_setprio 0
	v_add_f32_e32 v213, 0x41000000, v193
	s_cbranch_scc0 .LBB0_687
	s_waitcnt lgkmcnt(7)
	v_mfma_f32_32x32x16_bf16 v[32:47], v[140:143], v[96:99], 0
	s_waitcnt lgkmcnt(6)
	v_mfma_f32_32x32x16_bf16 v[32:47], v[136:139], v[100:103], v[32:47]
	s_waitcnt lgkmcnt(5)
	v_mfma_f32_32x32x16_bf16 v[32:47], v[132:135], v[104:107], v[32:47]
	s_waitcnt lgkmcnt(4)
	v_mfma_f32_32x32x16_bf16 v[32:47], v[128:131], v[108:111], v[32:47]
	s_waitcnt lgkmcnt(3)
	v_mfma_f32_32x32x16_bf16 v[64:79], v[144:147], v[96:99], 0
	s_nop 9
	v_max3_f32 v48, v32, s15, v33
	v_max3_f32 v48, v48, v34, v35
	v_max3_f32 v48, v48, v36, v37
	v_max3_f32 v48, v48, v38, v39
	v_max3_f32 v48, v48, v40, v41
	v_max3_f32 v48, v48, v42, v43
	v_max3_f32 v48, v48, v44, v45
	v_max3_f32 v48, v48, v46, v47
	v_mov_b32_e32 v49, v48
	v_mov_b32_e32 v50, v48
	s_nop 1
	v_permlane32_swap_b32_e32 v49, v50
	v_cndmask_b32_e64 v49, v49, v50, s[36:37]
	v_max_f32_e32 v49, v49, v49
	v_max_f32_e32 v48, v48, v49
	v_cmp_gt_f32_e32 vcc, v48, v213
	s_waitcnt lgkmcnt(2)
	v_mfma_f32_32x32x16_bf16 v[64:79], v[148:151], v[100:103], v[64:79]
	v_cndmask_b32_e32 v221, v193, v48, vcc
	v_max_f32_e32 v48, v221, v221
	v_max_f32_e32 v48, 0xefa18f08, v48
	v_sub_f32_e32 v32, v32, v48
	v_sub_f32_e32 v33, v33, v48
	v_exp_f32_e32 v80, v32
	v_sub_f32_e32 v34, v34, v48
	v_exp_f32_e32 v81, v33
	v_sub_f32_e32 v35, v35, v48
	v_exp_f32_e32 v82, v34
	v_sub_f32_e32 v36, v36, v48
	v_exp_f32_e32 v83, v35
	v_sub_f32_e32 v37, v37, v48
	v_exp_f32_e32 v84, v36
	v_add_f32_e32 v32, 0, v80
	v_sub_f32_e32 v38, v38, v48
	v_exp_f32_e32 v85, v37
	v_add_f32_e32 v32, v81, v32
	v_sub_f32_e32 v39, v39, v48
	v_exp_f32_e32 v86, v38
	s_waitcnt lgkmcnt(1)
	v_mfma_f32_32x32x16_bf16 v[64:79], v[152:155], v[104:107], v[64:79]
	v_add_f32_e32 v32, v82, v32
	v_sub_f32_e32 v40, v40, v48
	v_exp_f32_e32 v87, v39
	v_add_f32_e32 v32, v83, v32
	v_sub_f32_e32 v41, v41, v48
	v_exp_f32_e32 v88, v40
	v_add_f32_e32 v32, v84, v32
	v_sub_f32_e32 v42, v42, v48
	v_exp_f32_e32 v89, v41
	v_add_f32_e32 v32, v85, v32
	v_sub_f32_e32 v43, v43, v48
	v_exp_f32_e32 v90, v42
	v_add_f32_e32 v32, v86, v32
	v_sub_f32_e32 v44, v44, v48
	v_exp_f32_e32 v91, v43
	v_add_f32_e32 v32, v87, v32
	v_add_f32_e32 v32, v88, v32
	v_exp_f32_e32 v92, v44
	v_sub_f32_e32 v33, v45, v48
	v_add_f32_e32 v32, v89, v32
	v_exp_f32_e32 v93, v33
	v_sub_f32_e32 v33, v46, v48
	s_waitcnt lgkmcnt(0)
	v_mfma_f32_32x32x16_bf16 v[64:79], v[156:159], v[108:111], v[64:79]
	v_add_f32_e32 v32, v90, v32
	v_exp_f32_e32 v94, v33
	v_sub_f32_e32 v33, v47, v48
	v_add_f32_e32 v32, v91, v32
	v_exp_f32_e32 v95, v33
	v_add_f32_e32 v32, v92, v32
	v_sub_f32_e32 v49, v193, v221
	v_add_f32_e32 v32, v93, v32
	v_add_f32_e32 v32, v94, v32
	v_exp_f32_e32 v164, v49
	v_add_f32_e32 v214, v95, v32
	v_mov_b32_e32 v215, v214
	v_mov_b32_e32 v216, v214
	s_nop 0
	s_nop 0
	v_permlane32_swap_b32_e32 v215, v216
	v_cmp_neq_f32_e32 vcc, v221, v193
	s_cbranch_vccz .LBB0_680
	v_pk_mul_f32 v[30:31], v[30:31], v[164:165] op_sel_hi:[1,0]
	v_pk_mul_f32 v[28:29], v[28:29], v[164:165] op_sel_hi:[1,0]
	v_pk_mul_f32 v[26:27], v[26:27], v[164:165] op_sel_hi:[1,0]
	v_pk_mul_f32 v[24:25], v[24:25], v[164:165] op_sel_hi:[1,0]
	v_pk_mul_f32 v[22:23], v[22:23], v[164:165] op_sel_hi:[1,0]
	v_pk_mul_f32 v[20:21], v[20:21], v[164:165] op_sel_hi:[1,0]
	v_pk_mul_f32 v[18:19], v[18:19], v[164:165] op_sel_hi:[1,0]
	v_pk_mul_f32 v[16:17], v[16:17], v[164:165] op_sel_hi:[1,0]
	v_pk_mul_f32 v[14:15], v[14:15], v[164:165] op_sel_hi:[1,0]
	v_pk_mul_f32 v[12:13], v[12:13], v[164:165] op_sel_hi:[1,0]
	v_pk_mul_f32 v[10:11], v[10:11], v[164:165] op_sel_hi:[1,0]
	v_pk_mul_f32 v[8:9], v[8:9], v[164:165] op_sel_hi:[1,0]
	v_pk_mul_f32 v[6:7], v[6:7], v[164:165] op_sel_hi:[1,0]
	v_pk_mul_f32 v[4:5], v[4:5], v[164:165] op_sel_hi:[1,0]
	v_pk_mul_f32 v[2:3], v[2:3], v[164:165] op_sel_hi:[1,0]
	v_pk_mul_f32 v[0:1], v[0:1], v[164:165] op_sel_hi:[1,0]
; #define LAS __attribute__((address_space(3)))
; DI float ex2(float x) { return __builtin_amdgcn_exp2f(x); }
; template <int MM> DI void smax_step_nb(const f32x16& s, unsigned vm, float& m, float& l, f32x16 (&o)[2], bf16x8 (&pf)[2], int lane) {
;     float mx = -1e30f;
; #pragma unroll
;     for (int i = 0; i < 16; ++i) mx = fmaxf(mx, s[i]);
;     if (MM == 1) mx = vm ? mx : -1e30f;
;     mx = fmaxf(mx, shx32(mx, lane));
;     const float mn = (mx > m + 8.0f) ? mx : m;
;     float mref = fmaxf(mn, -1e29f);
;     if (MM == 1) mref = vm ? mref : 3e38f;
;     const float alpha = ex2(m - mn);
;     float p[16], rs = 0.f;
; #pragma unroll
;     for (int i = 0; i < 16; ++i) { p[i] = ex2(s[i] - mref); rs += p[i]; }
;     rs += shx32(rs, lane);
;     l = l * alpha + rs;
;     if (__builtin_amdgcn_ballot_w64(mn != m) != 0ull) {
; #pragma unroll
;         for (int i = 0; i < 16; ++i) { o[0][i] *= alpha; o[1][i] *= alpha; }
;     }
;     m = mn;
;     pack_p(p, pf);
; }
; template <int MM> DI void tile128_pipe(LAS const char* K0, LAS const char* V0, LAS const char* K1, LAS const char* V1, const bf16x8 (&qf)[4], unsigned vm0, unsigned vm1,
;                                        float& m, float& l, f32x16 (&o)[2], int r, int h, int lane) {
;     f32x16 sa = qk_rows<0, 4>(K0, 0, qf, r, h), sb = qk_rows<0, 4>(K0, 32, qf, r, h);
;     bf16x8 pfa[2], pfb[2];
;     smax_step_nb<MM>(sa, vm0, m, l, o, pfa, lane);
;     sa = qk_rows<0, 4>(K1, 0, qf, r, h);
;     pv_rows(o, V0, 0, pfa, lane);
;     smax_step_nb<MM>(sb, vm0, m, l, o, pfb, lane);
;     sb = qk_rows<0, 4>(K1, 32, qf, r, h);
;     pv_rows(o, V0, 32, pfb, lane);
;     smax_step_nb<MM>(sa, vm1, m, l, o, pfa, lane);
;     pv_rows(o, V1, 0, pfa, lane);
;     smax_step_nb<MM>(sb, vm1, m, l, o, pfb, lane);
;     pv_rows(o, V1, 32, pfb, lane);
; }
.LBB0_680:
	v_cvt_pk_bf16_f32 v222, v80, v81
	v_cvt_pk_bf16_f32 v223, v82, v83
	ds_read_b128 v[80:83], v212 offset:18432
	ds_read_b128 v[230:233], v212 offset:18464
	ds_read_b128 v[234:237], v212 offset:18496
	ds_read_b128 v[238:241], v212 offset:18528
	v_cvt_pk_bf16_f32 v224, v84, v85
	v_cvt_pk_bf16_f32 v225, v86, v87
	v_cvt_pk_bf16_f32 v226, v88, v89
	v_cvt_pk_bf16_f32 v227, v90, v91
	v_cvt_pk_bf16_f32 v228, v92, v93
	v_cvt_pk_bf16_f32 v229, v94, v95
	s_setprio 1
	s_waitcnt lgkmcnt(3)
	v_mfma_f32_32x32x16_bf16 v[80:95], v[80:83], v[96:99], 0
	s_waitcnt lgkmcnt(2)
	v_mfma_f32_32x32x16_bf16 v[80:95], v[230:233], v[100:103], v[80:95]
	s_waitcnt lgkmcnt(1)
	v_mfma_f32_32x32x16_bf16 v[80:95], v[234:237], v[104:107], v[80:95]
	s_waitcnt lgkmcnt(0)
	v_mfma_f32_32x32x16_bf16 v[80:95], v[238:241], v[108:111], v[80:95]
	s_setprio 0
	v_add3_u32 v166, s10, v191, v171
	v_add_u32_e32 v217, v166, v186
	ds_read_b64_tr_b16 v[230:231], v217 offset:9216
	ds_read_b64_tr_b16 v[232:233], v217 offset:10368
	ds_read_b64_tr_b16 v[236:237], v217 offset:10432
	ds_read_b64_tr_b16 v[234:235], v217 offset:9280
	ds_read_b64_tr_b16 v[238:239], v217 offset:11520
	ds_read_b64_tr_b16 v[240:241], v217 offset:12672
	ds_read_b64_tr_b16 v[244:245], v217 offset:12736
	ds_read_b64_tr_b16 v[242:243], v217 offset:11584
	s_setprio 1
	s_waitcnt lgkmcnt(6)
	v_mfma_f32_32x32x16_bf16 v[0:15], v[230:233], v[222:225], v[0:15]
	s_waitcnt lgkmcnt(4)
	v_mfma_f32_32x32x16_bf16 v[16:31], v[234:237], v[222:225], v[16:31]
	s_waitcnt lgkmcnt(2)
	v_mfma_f32_32x32x16_bf16 v[0:15], v[238:241], v[226:229], v[0:15]
	s_waitcnt lgkmcnt(0)
	v_mfma_f32_32x32x16_bf16 v[16:31], v[242:245], v[226:229], v[16:31]
	s_setprio 0
	v_max3_f32 v166, v64, s15, v65
	v_max3_f32 v166, v166, v66, v67
	v_max3_f32 v166, v166, v68, v69
	v_max3_f32 v166, v166, v70, v71
	v_max3_f32 v166, v166, v72, v73
	v_max3_f32 v166, v166, v74, v75
	v_max3_f32 v166, v166, v76, v77
	v_max3_f32 v166, v166, v78, v79
	v_mov_b32_e32 v172, v166
	v_mov_b32_e32 v173, v166
	s_nop 1
	v_permlane32_swap_b32_e32 v172, v173
	v_cndmask_b32_e64 v172, v172, v173, s[36:37]
	v_max_f32_e32 v172, v172, v172
	v_max_f32_e32 v166, v166, v172
	v_add_f32_e32 v172, 0x41000000, v221
	v_cmp_gt_f32_e32 vcc, v166, v172
	s_nop 1
	v_cndmask_b32_e32 v222, v221, v166, vcc
	v_max_f32_e32 v166, v222, v222
	v_max_f32_e32 v166, 0xefa18f08, v166
	v_sub_f32_e32 v64, v64, v166
	v_exp_f32_e32 v64, v64
	v_sub_f32_e32 v65, v65, v166
	v_exp_f32_e32 v65, v65
	v_sub_f32_e32 v66, v66, v166
	v_exp_f32_e32 v66, v66
	v_sub_f32_e32 v67, v67, v166
	v_exp_f32_e32 v67, v67
	v_sub_f32_e32 v68, v68, v166
	v_add_f32_e32 v173, 0, v64
	v_exp_f32_e32 v68, v68
	v_sub_f32_e32 v69, v69, v166
	v_add_f32_e32 v173, v65, v173
	v_exp_f32_e32 v69, v69
	v_sub_f32_e32 v70, v70, v166
	v_add_f32_e32 v173, v66, v173
	v_exp_f32_e32 v70, v70
	v_sub_f32_e32 v71, v71, v166
	v_add_f32_e32 v173, v67, v173
	v_exp_f32_e32 v71, v71
	v_sub_f32_e32 v72, v72, v166
	v_add_f32_e32 v173, v68, v173
	v_exp_f32_e32 v72, v72
	v_sub_f32_e32 v73, v73, v166
	v_add_f32_e32 v173, v69, v173
	v_exp_f32_e32 v73, v73
	v_sub_f32_e32 v74, v74, v166
	v_add_f32_e32 v173, v70, v173
	v_exp_f32_e32 v74, v74
	v_sub_f32_e32 v75, v75, v166
	v_add_f32_e32 v173, v71, v173
	v_exp_f32_e32 v75, v75
	v_sub_f32_e32 v76, v76, v166
	v_add_f32_e32 v173, v72, v173
	v_exp_f32_e32 v76, v76
	v_sub_f32_e32 v77, v77, v166
	v_add_f32_e32 v173, v73, v173
	v_exp_f32_e32 v77, v77
	v_sub_f32_e32 v78, v78, v166
	v_add_f32_e32 v173, v74, v173
	v_exp_f32_e32 v78, v78
	v_sub_f32_e32 v79, v79, v166
	v_add_f32_e32 v173, v75, v173
	v_exp_f32_e32 v79, v79
	v_add_f32_e32 v166, v76, v173
	v_add_f32_e32 v166, v77, v166
	v_sub_f32_e32 v172, v221, v222
	v_add_f32_e32 v166, v78, v166
	v_add_f32_e32 v218, v79, v166
	v_exp_f32_e32 v166, v172
	v_mov_b32_e32 v219, v218
	v_mov_b32_e32 v220, v218
	s_nop 1
	v_permlane32_swap_b32_e32 v219, v220
	v_cmp_neq_f32_e32 vcc, v222, v221
	s_cbranch_vccz .LBB0_682
	v_pk_mul_f32 v[30:31], v[30:31], v[166:167] op_sel_hi:[1,0]
	v_pk_mul_f32 v[28:29], v[28:29], v[166:167] op_sel_hi:[1,0]
	v_pk_mul_f32 v[26:27], v[26:27], v[166:167] op_sel_hi:[1,0]
	v_pk_mul_f32 v[24:25], v[24:25], v[166:167] op_sel_hi:[1,0]
	v_pk_mul_f32 v[22:23], v[22:23], v[166:167] op_sel_hi:[1,0]
	v_pk_mul_f32 v[20:21], v[20:21], v[166:167] op_sel_hi:[1,0]
	v_pk_mul_f32 v[18:19], v[18:19], v[166:167] op_sel_hi:[1,0]
	v_pk_mul_f32 v[16:17], v[16:17], v[166:167] op_sel_hi:[1,0]
	v_pk_mul_f32 v[14:15], v[14:15], v[166:167] op_sel_hi:[1,0]
	v_pk_mul_f32 v[12:13], v[12:13], v[166:167] op_sel_hi:[1,0]
	v_pk_mul_f32 v[10:11], v[10:11], v[166:167] op_sel_hi:[1,0]
	v_pk_mul_f32 v[8:9], v[8:9], v[166:167] op_sel_hi:[1,0]
	v_pk_mul_f32 v[6:7], v[6:7], v[166:167] op_sel_hi:[1,0]
	v_pk_mul_f32 v[4:5], v[4:5], v[166:167] op_sel_hi:[1,0]
	v_pk_mul_f32 v[2:3], v[2:3], v[166:167] op_sel_hi:[1,0]
	v_pk_mul_f32 v[0:1], v[0:1], v[166:167] op_sel_hi:[1,0]
; #define LAS __attribute__((address_space(3)))
; DI float ex2(float x) { return __builtin_amdgcn_exp2f(x); }
; template <int MM> DI void smax_step_nb(const f32x16& s, unsigned vm, float& m, float& l, f32x16 (&o)[2], bf16x8 (&pf)[2], int lane) {
;     float mx = -1e30f;
; #pragma unroll
;     for (int i = 0; i < 16; ++i) mx = fmaxf(mx, s[i]);
;     if (MM == 1) mx = vm ? mx : -1e30f;
;     mx = fmaxf(mx, shx32(mx, lane));
;     const float mn = (mx > m + 8.0f) ? mx : m;
;     float mref = fmaxf(mn, -1e29f);
;     if (MM == 1) mref = vm ? mref : 3e38f;
;     const float alpha = ex2(m - mn);
;     float p[16], rs = 0.f;
; #pragma unroll
;     for (int i = 0; i < 16; ++i) { p[i] = ex2(s[i] - mref); rs += p[i]; }
;     rs += shx32(rs, lane);
;     l = l * alpha + rs;
;     if (__builtin_amdgcn_ballot_w64(mn != m) != 0ull) {
; #pragma unroll
;         for (int i = 0; i < 16; ++i) { o[0][i] *= alpha; o[1][i] *= alpha; }
;     }
;     m = mn;
;     pack_p(p, pf);
; }
; template <int MM> DI void tile128_pipe(LAS const char* K0, LAS const char* V0, LAS const char* K1, LAS const char* V1, const bf16x8 (&qf)[4], unsigned vm0, unsigned vm1,
;                                        float& m, float& l, f32x16 (&o)[2], int r, int h, int lane) {
;     f32x16 sa = qk_rows<0, 4>(K0, 0, qf, r, h), sb = qk_rows<0, 4>(K0, 32, qf, r, h);
;     bf16x8 pfa[2], pfb[2];
;     smax_step_nb<MM>(sa, vm0, m, l, o, pfa, lane);
;     sa = qk_rows<0, 4>(K1, 0, qf, r, h);
;     pv_rows(o, V0, 0, pfa, lane);
;     smax_step_nb<MM>(sb, vm0, m, l, o, pfb, lane);
;     sb = qk_rows<0, 4>(K1, 32, qf, r, h);
;     pv_rows(o, V0, 32, pfb, lane);
;     smax_step_nb<MM>(sa, vm1, m, l, o, pfa, lane);
;     pv_rows(o, V1, 0, pfa, lane);
;     smax_step_nb<MM>(sb, vm1, m, l, o, pfb, lane);
;     pv_rows(o, V1, 32, pfb, lane);
; }
.LBB0_682:
	v_cvt_pk_bf16_f32 v224, v64, v65
	v_cvt_pk_bf16_f32 v225, v66, v67
	ds_read_b128 v[64:67], v212 offset:23040
	ds_read_b128 v[232:235], v212 offset:23072
	ds_read_b128 v[236:239], v212 offset:23104
	ds_read_b128 v[240:243], v212 offset:23136
	v_cvt_pk_bf16_f32 v226, v68, v69
	v_cvt_pk_bf16_f32 v227, v70, v71
	v_cvt_pk_bf16_f32 v228, v72, v73
	v_cvt_pk_bf16_f32 v229, v74, v75
	v_cvt_pk_bf16_f32 v230, v76, v77
	v_cvt_pk_bf16_f32 v231, v78, v79
	s_setprio 1
	s_waitcnt lgkmcnt(3)
	v_mfma_f32_32x32x16_bf16 v[64:79], v[64:67], v[96:99], 0
	s_waitcnt lgkmcnt(2)
	v_mfma_f32_32x32x16_bf16 v[64:79], v[232:235], v[100:103], v[64:79]
	s_waitcnt lgkmcnt(1)
	v_mfma_f32_32x32x16_bf16 v[64:79], v[236:239], v[104:107], v[64:79]
	s_waitcnt lgkmcnt(0)
	v_mfma_f32_32x32x16_bf16 v[64:79], v[240:243], v[108:111], v[64:79]
	s_setprio 0
	ds_read_b64_tr_b16 v[232:233], v217 offset:13824
	ds_read_b64_tr_b16 v[234:235], v217 offset:14976
	ds_read_b64_tr_b16 v[238:239], v217 offset:15040
	ds_read_b64_tr_b16 v[236:237], v217 offset:13888
	ds_read_b64_tr_b16 v[240:241], v217 offset:16128
	ds_read_b64_tr_b16 v[242:243], v217 offset:17280
	ds_read_b64_tr_b16 v[246:247], v217 offset:17344
	ds_read_b64_tr_b16 v[244:245], v217 offset:16192
	s_setprio 1
	s_waitcnt lgkmcnt(6)
	v_mfma_f32_32x32x16_bf16 v[0:15], v[232:235], v[224:227], v[0:15]
	s_waitcnt lgkmcnt(4)
	v_mfma_f32_32x32x16_bf16 v[16:31], v[236:239], v[224:227], v[16:31]
	s_waitcnt lgkmcnt(2)
	v_mfma_f32_32x32x16_bf16 v[0:15], v[240:243], v[228:231], v[0:15]
	s_waitcnt lgkmcnt(0)
	v_mfma_f32_32x32x16_bf16 v[16:31], v[244:247], v[228:231], v[16:31]
	s_setprio 0
	v_max3_f32 v172, v80, s15, v81
	v_max3_f32 v172, v172, v82, v83
	v_max3_f32 v172, v172, v84, v85
	v_max3_f32 v172, v172, v86, v87
	v_max3_f32 v172, v172, v88, v89
	v_max3_f32 v172, v172, v90, v91
	v_max3_f32 v172, v172, v92, v93
	v_max3_f32 v172, v172, v94, v95
	v_mov_b32_e32 v173, v172
	v_mov_b32_e32 v206, v172
	s_nop 1
	v_permlane32_swap_b32_e32 v173, v206
	v_cndmask_b32_e64 v173, v173, v206, s[36:37]
	v_max_f32_e32 v173, v173, v173
	v_max_f32_e32 v172, v172, v173
	v_add_f32_e32 v173, 0x41000000, v222
	v_cmp_gt_f32_e32 vcc, v172, v173
	s_nop 1
	v_cndmask_b32_e32 v221, v222, v172, vcc
	v_max_f32_e32 v172, v221, v221
	v_max_f32_e32 v172, 0xefa18f08, v172
	v_sub_f32_e32 v80, v80, v172
	v_exp_f32_e32 v223, v80
	v_sub_f32_e32 v80, v81, v172
	v_exp_f32_e32 v81, v80
	v_sub_f32_e32 v80, v82, v172
	v_exp_f32_e32 v224, v80
	v_sub_f32_e32 v80, v83, v172
	v_exp_f32_e32 v225, v80
	v_sub_f32_e32 v82, v84, v172
	v_add_f32_e32 v80, 0, v223
	v_exp_f32_e32 v226, v82
	v_sub_f32_e32 v82, v85, v172
	v_add_f32_e32 v80, v81, v80
	v_exp_f32_e32 v85, v82
	v_sub_f32_e32 v82, v86, v172
	v_add_f32_e32 v80, v224, v80
	v_exp_f32_e32 v86, v82
	v_sub_f32_e32 v82, v87, v172
	v_add_f32_e32 v80, v225, v80
	v_exp_f32_e32 v87, v82
	v_sub_f32_e32 v82, v88, v172
	v_add_f32_e32 v80, v226, v80
	v_exp_f32_e32 v88, v82
	v_sub_f32_e32 v82, v89, v172
	v_add_f32_e32 v80, v85, v80
	v_exp_f32_e32 v89, v82
	v_sub_f32_e32 v82, v90, v172
	v_add_f32_e32 v80, v86, v80
	v_exp_f32_e32 v90, v82
	v_sub_f32_e32 v82, v91, v172
	v_add_f32_e32 v80, v87, v80
	v_exp_f32_e32 v91, v82
	v_sub_f32_e32 v82, v92, v172
	v_add_f32_e32 v80, v88, v80
	v_exp_f32_e32 v92, v82
	v_sub_f32_e32 v82, v93, v172
	v_add_f32_e32 v80, v89, v80
	v_exp_f32_e32 v93, v82
	v_sub_f32_e32 v82, v94, v172
	v_add_f32_e32 v80, v90, v80
	v_exp_f32_e32 v94, v82
	v_sub_f32_e32 v82, v95, v172
	v_add_f32_e32 v80, v91, v80
	v_exp_f32_e32 v95, v82
	v_add_f32_e32 v80, v92, v80
	v_add_f32_e32 v80, v93, v80
	v_sub_f32_e32 v173, v222, v221
	v_add_f32_e32 v80, v94, v80
	v_add_f32_e32 v82, v95, v80
	v_exp_f32_e32 v80, v173
	v_mov_b32_e32 v83, v82
	v_mov_b32_e32 v84, v82
	s_nop 1
	v_permlane32_swap_b32_e32 v83, v84
	v_cmp_neq_f32_e32 vcc, v221, v222
	s_cbranch_vccz .LBB0_684
	v_pk_mul_f32 v[30:31], v[30:31], v[80:81] op_sel_hi:[1,0]
	v_pk_mul_f32 v[28:29], v[28:29], v[80:81] op_sel_hi:[1,0]
	v_pk_mul_f32 v[26:27], v[26:27], v[80:81] op_sel_hi:[1,0]
	v_pk_mul_f32 v[24:25], v[24:25], v[80:81] op_sel_hi:[1,0]
	v_pk_mul_f32 v[22:23], v[22:23], v[80:81] op_sel_hi:[1,0]
	v_pk_mul_f32 v[20:21], v[20:21], v[80:81] op_sel_hi:[1,0]
	v_pk_mul_f32 v[18:19], v[18:19], v[80:81] op_sel_hi:[1,0]
	v_pk_mul_f32 v[16:17], v[16:17], v[80:81] op_sel_hi:[1,0]
	v_pk_mul_f32 v[14:15], v[14:15], v[80:81] op_sel_hi:[1,0]
	v_pk_mul_f32 v[12:13], v[12:13], v[80:81] op_sel_hi:[1,0]
	v_pk_mul_f32 v[10:11], v[10:11], v[80:81] op_sel_hi:[1,0]
	v_pk_mul_f32 v[8:9], v[8:9], v[80:81] op_sel_hi:[1,0]
	v_pk_mul_f32 v[6:7], v[6:7], v[80:81] op_sel_hi:[1,0]
	v_pk_mul_f32 v[4:5], v[4:5], v[80:81] op_sel_hi:[1,0]
	v_pk_mul_f32 v[2:3], v[2:3], v[80:81] op_sel_hi:[1,0]
	v_pk_mul_f32 v[0:1], v[0:1], v[80:81] op_sel_hi:[1,0]
; #define LAS __attribute__((address_space(3)))
; DI float ex2(float x) { return __builtin_amdgcn_exp2f(x); }
; template <int MM> DI void smax_step_nb(const f32x16& s, unsigned vm, float& m, float& l, f32x16 (&o)[2], bf16x8 (&pf)[2], int lane) {
;     float mx = -1e30f;
; #pragma unroll
;     for (int i = 0; i < 16; ++i) mx = fmaxf(mx, s[i]);
;     if (MM == 1) mx = vm ? mx : -1e30f;
;     mx = fmaxf(mx, shx32(mx, lane));
;     const float mn = (mx > m + 8.0f) ? mx : m;
;     float mref = fmaxf(mn, -1e29f);
;     if (MM == 1) mref = vm ? mref : 3e38f;
;     const float alpha = ex2(m - mn);
;     float p[16], rs = 0.f;
; #pragma unroll
;     for (int i = 0; i < 16; ++i) { p[i] = ex2(s[i] - mref); rs += p[i]; }
;     rs += shx32(rs, lane);
;     l = l * alpha + rs;
;     if (__builtin_amdgcn_ballot_w64(mn != m) != 0ull) {
; #pragma unroll
;         for (int i = 0; i < 16; ++i) { o[0][i] *= alpha; o[1][i] *= alpha; }
;     }
;     m = mn;
;     pack_p(p, pf);
; }
; template <int MM> DI void tile128_pipe(LAS const char* K0, LAS const char* V0, LAS const char* K1, LAS const char* V1, const bf16x8 (&qf)[4], unsigned vm0, unsigned vm1,
;                                        float& m, float& l, f32x16 (&o)[2], int r, int h, int lane) {
;     f32x16 sa = qk_rows<0, 4>(K0, 0, qf, r, h), sb = qk_rows<0, 4>(K0, 32, qf, r, h);
;     bf16x8 pfa[2], pfb[2];
;     smax_step_nb<MM>(sa, vm0, m, l, o, pfa, lane);
;     sa = qk_rows<0, 4>(K1, 0, qf, r, h);
;     pv_rows(o, V0, 0, pfa, lane);
;     smax_step_nb<MM>(sb, vm0, m, l, o, pfb, lane);
;     sb = qk_rows<0, 4>(K1, 32, qf, r, h);
;     pv_rows(o, V0, 32, pfb, lane);
;     smax_step_nb<MM>(sa, vm1, m, l, o, pfa, lane);
;     pv_rows(o, V1, 0, pfa, lane);
;     smax_step_nb<MM>(sb, vm1, m, l, o, pfb, lane);
;     pv_rows(o, V1, 32, pfb, lane);
; }
.LBB0_684:
	v_cvt_pk_bf16_f32 v222, v223, v81
	v_cvt_pk_bf16_f32 v223, v224, v225
	v_cvt_pk_bf16_f32 v224, v226, v85
	v_cvt_pk_bf16_f32 v225, v86, v87
	v_cvt_pk_bf16_f32 v86, v88, v89
	v_cvt_pk_bf16_f32 v87, v90, v91
	v_cvt_pk_bf16_f32 v88, v92, v93
	ds_read_b64_tr_b16 v[90:91], v217 offset:27648
	ds_read_b64_tr_b16 v[92:93], v217 offset:28800
	ds_read_b64_tr_b16 v[226:227], v217 offset:29952
	ds_read_b64_tr_b16 v[228:229], v217 offset:31104
	ds_read_b64_tr_b16 v[230:231], v217 offset:27712
	ds_read_b64_tr_b16 v[232:233], v217 offset:28864
	ds_read_b64_tr_b16 v[234:235], v217 offset:30016
	ds_read_b64_tr_b16 v[236:237], v217 offset:31168
	v_cvt_pk_bf16_f32 v89, v94, v95
	s_setprio 1
	s_waitcnt lgkmcnt(6)
	v_mfma_f32_32x32x16_bf16 v[0:15], v[90:93], v[222:225], v[0:15]
	s_waitcnt lgkmcnt(2)
	v_mfma_f32_32x32x16_bf16 v[16:31], v[230:233], v[222:225], v[16:31]
	v_mfma_f32_32x32x16_bf16 v[0:15], v[226:229], v[86:89], v[0:15]
	s_waitcnt lgkmcnt(0)
	v_mfma_f32_32x32x16_bf16 v[16:31], v[234:237], v[86:89], v[16:31]
	s_setprio 0
	v_max3_f32 v81, v64, s15, v65
	v_max3_f32 v81, v81, v66, v67
	v_max3_f32 v81, v81, v68, v69
	v_max3_f32 v81, v81, v70, v71
	v_max3_f32 v81, v81, v72, v73
	v_max3_f32 v81, v81, v74, v75
	v_max3_f32 v81, v81, v76, v77
	v_max3_f32 v81, v81, v78, v79
	v_mov_b32_e32 v85, v81
	v_mov_b32_e32 v86, v81
	s_nop 1
	v_permlane32_swap_b32_e32 v85, v86
	v_cndmask_b32_e64 v85, v85, v86, s[36:37]
	v_max_f32_e32 v85, v85, v85
	v_max_f32_e32 v81, v81, v85
	v_add_f32_e32 v85, 0x41000000, v221
	v_cmp_gt_f32_e32 vcc, v81, v85
	s_nop 1
	v_cndmask_b32_e32 v81, v221, v81, vcc
	v_max_f32_e32 v85, v81, v81
	v_max_f32_e32 v93, 0xefa18f08, v85
	v_sub_f32_e32 v64, v64, v93
	v_exp_f32_e32 v85, v64
	v_sub_f32_e32 v64, v65, v93
	v_exp_f32_e32 v86, v64
	v_sub_f32_e32 v64, v66, v93
	v_exp_f32_e32 v87, v64
	v_sub_f32_e32 v64, v67, v93
	v_exp_f32_e32 v88, v64
	v_sub_f32_e32 v65, v68, v93
	v_add_f32_e32 v64, 0, v85
	v_exp_f32_e32 v89, v65
	v_sub_f32_e32 v65, v69, v93
	v_add_f32_e32 v64, v86, v64
	v_exp_f32_e32 v90, v65
	v_sub_f32_e32 v65, v70, v93
	v_add_f32_e32 v64, v87, v64
	v_exp_f32_e32 v91, v65
	v_sub_f32_e32 v65, v71, v93
	v_add_f32_e32 v64, v88, v64
	v_exp_f32_e32 v92, v65
	v_sub_f32_e32 v65, v72, v93
	v_add_f32_e32 v64, v89, v64
	v_exp_f32_e32 v66, v65
	v_sub_f32_e32 v65, v73, v93
	v_add_f32_e32 v64, v90, v64
	v_exp_f32_e32 v67, v65
	v_sub_f32_e32 v65, v74, v93
	v_add_f32_e32 v64, v91, v64
	v_exp_f32_e32 v68, v65
	v_sub_f32_e32 v65, v75, v93
	v_add_f32_e32 v64, v92, v64
	v_exp_f32_e32 v69, v65
	v_sub_f32_e32 v65, v76, v93
	v_add_f32_e32 v64, v66, v64
	v_exp_f32_e32 v70, v65
	v_sub_f32_e32 v65, v77, v93
	v_add_f32_e32 v64, v67, v64
	v_exp_f32_e32 v71, v65
	v_sub_f32_e32 v65, v78, v93
	v_add_f32_e32 v64, v68, v64
	v_exp_f32_e32 v72, v65
	v_sub_f32_e32 v65, v79, v93
	v_add_f32_e32 v64, v69, v64
	v_exp_f32_e32 v73, v65
	v_add_f32_e32 v64, v70, v64
	v_add_f32_e32 v64, v71, v64
	v_sub_f32_e32 v94, v221, v81
	v_add_f32_e32 v64, v72, v64
	v_add_f32_e32 v65, v73, v64
	v_exp_f32_e32 v64, v94
	v_mov_b32_e32 v74, v65
	v_mov_b32_e32 v75, v65
	s_nop 1
	v_permlane32_swap_b32_e32 v74, v75
	v_cmp_neq_f32_e32 vcc, v81, v221
	s_cbranch_vccz .LBB0_686
	v_pk_mul_f32 v[30:31], v[30:31], v[64:65] op_sel_hi:[1,0]
	v_pk_mul_f32 v[28:29], v[28:29], v[64:65] op_sel_hi:[1,0]
	v_pk_mul_f32 v[26:27], v[26:27], v[64:65] op_sel_hi:[1,0]
	v_pk_mul_f32 v[24:25], v[24:25], v[64:65] op_sel_hi:[1,0]
	v_pk_mul_f32 v[22:23], v[22:23], v[64:65] op_sel_hi:[1,0]
	v_pk_mul_f32 v[20:21], v[20:21], v[64:65] op_sel_hi:[1,0]
	v_pk_mul_f32 v[18:19], v[18:19], v[64:65] op_sel_hi:[1,0]
	v_pk_mul_f32 v[16:17], v[16:17], v[64:65] op_sel_hi:[1,0]
	v_pk_mul_f32 v[14:15], v[14:15], v[64:65] op_sel_hi:[1,0]
	v_pk_mul_f32 v[12:13], v[12:13], v[64:65] op_sel_hi:[1,0]
	v_pk_mul_f32 v[10:11], v[10:11], v[64:65] op_sel_hi:[1,0]
	v_pk_mul_f32 v[8:9], v[8:9], v[64:65] op_sel_hi:[1,0]
	v_pk_mul_f32 v[6:7], v[6:7], v[64:65] op_sel_hi:[1,0]
	v_pk_mul_f32 v[4:5], v[4:5], v[64:65] op_sel_hi:[1,0]
	v_pk_mul_f32 v[2:3], v[2:3], v[64:65] op_sel_hi:[1,0]
	v_pk_mul_f32 v[0:1], v[0:1], v[64:65] op_sel_hi:[1,0]
.LBB0_686:
	v_cndmask_b32_e64 v76, v215, v216, s[36:37]
	v_add_f32_e32 v76, v214, v76
	v_cndmask_b32_e64 v77, v219, v220, s[36:37]
	v_fmac_f32_e32 v76, v184, v164
	v_add_f32_e32 v77, v218, v77
	v_fmac_f32_e32 v77, v76, v166
	v_cndmask_b32_e64 v76, v83, v84, s[36:37]
	v_add_f32_e32 v76, v82, v76
	v_cndmask_b32_e64 v74, v74, v75, s[36:37]
	v_fmac_f32_e32 v76, v77, v80
	v_add_f32_e32 v65, v65, v74
	v_fmac_f32_e32 v65, v76, v64
	v_cvt_pk_bf16_f32 v74, v85, v86
	v_cvt_pk_bf16_f32 v75, v87, v88
	v_cvt_pk_bf16_f32 v76, v89, v90
	v_cvt_pk_bf16_f32 v77, v91, v92
	ds_read_b64_tr_b16 v[84:85], v217 offset:33408
	ds_read_b64_tr_b16 v[86:87], v217 offset:34560
	ds_read_b64_tr_b16 v[90:91], v217 offset:34624
	ds_read_b64_tr_b16 v[220:221], v217 offset:33472
	ds_read_b64_tr_b16 v[82:83], v217 offset:32256
	ds_read_b64_tr_b16 v[88:89], v217 offset:35712
	ds_read_b64_tr_b16 v[218:219], v217 offset:32320
	ds_read_b64_tr_b16 v[92:93], v217 offset:35776
	v_cvt_pk_bf16_f32 v66, v66, v67
	v_cvt_pk_bf16_f32 v67, v68, v69
	v_cvt_pk_bf16_f32 v68, v70, v71
	v_cvt_pk_bf16_f32 v69, v72, v73
	s_setprio 1
	s_waitcnt lgkmcnt(3)
	v_mfma_f32_32x32x16_bf16 v[0:15], v[82:85], v[74:77], v[0:15]
	s_waitcnt lgkmcnt(1)
	v_mfma_f32_32x32x16_bf16 v[16:31], v[218:221], v[74:77], v[16:31]
	v_mfma_f32_32x32x16_bf16 v[0:15], v[86:89], v[66:69], v[0:15]
	s_waitcnt lgkmcnt(0)
	v_mfma_f32_32x32x16_bf16 v[16:31], v[90:93], v[66:69], v[16:31]
	s_branch .LBB0_697

; #define LAS __attribute__((address_space(3)))
; template <int MODE, bool PRE = false> ...
;     ...
;                 if (b0 != 0ull && b1 != 0ull) {
;                     LAS char* K0 = lds + (sti & 1) * 4 * TILE_B;
;                     if ((b0 & b1) == ~0ull) tile128_pipe<0>(K0, K0 + TILE_B, K0 + 2 * TILE_B, K0 + 3 * TILE_B, qf, 1u, 1u, m1, l1, o1, r, h, lane);
;                     else tile128_pipe<1>(K0, K0 + TILE_B, K0 + 2 * TILE_B, K0 + 3 * TILE_B, qf, ls0 ? 1u : 0u, ls1 ? 1u : 0u, m1, l1, o1, r, h, lane);
;                     goto step_done;
;                 }
.LBB0_697:
	s_setprio 0
	s_mov_b32 s0, 9
	v_mov_b32_e32 v184, v65
	v_mov_b32_e32 v193, v81

; #define LAS __attribute__((address_space(3)))
; DI float ex2(float x) { return __builtin_amdgcn_exp2f(x); }
; template <int MM> DI void smax_step_nb(const f32x16& s, unsigned vm, float& m, float& l, f32x16 (&o)[2], bf16x8 (&pf)[2], int lane) {
;     float mx = -1e30f;
; #pragma unroll
;     for (int i = 0; i < 16; ++i) mx = fmaxf(mx, s[i]);
;     if (MM == 1) mx = vm ? mx : -1e30f;
;     mx = fmaxf(mx, shx32(mx, lane));
;     const float mn = (mx > m + 8.0f) ? mx : m;
;     float mref = fmaxf(mn, -1e29f);
;     if (MM == 1) mref = vm ? mref : 3e38f;
;     const float alpha = ex2(m - mn);
;     float p[16], rs = 0.f;
; #pragma unroll
;     for (int i = 0; i < 16; ++i) { p[i] = ex2(s[i] - mref); rs += p[i]; }
;     rs += shx32(rs, lane);
;     l = l * alpha + rs;
;     if (__builtin_amdgcn_ballot_w64(mn != m) != 0ull) {
; #pragma unroll
;         for (int i = 0; i < 16; ++i) { o[0][i] *= alpha; o[1][i] *= alpha; }
;     }
;     m = mn;
;     pack_p(p, pf);
; }
; template <int MODE, bool PRE = false> ...
;     ...
;         if (MODE != MODE_DIFF) {
;             const int kt0 = kt_lo + 2 * sti;
;             bool both = (kt0 + 1 <= kt_hi) && (64 * kt0 + 127 <= q0w);
;             if (MODE == MODE_NWIN) both = both && (64 * kt0 > q0w + 31 - 512);
;             if (both) {
;                 bool ls0 = true, ls1 = true;
;                 if (MODE == MODE_MOBA) { ls0 = ((sel >> (kt0 >> 2)) & 1ull) != 0ull; ls1 = ((sel >> ((kt0 + 1) >> 2)) & 1ull) != 0ull; }
;                 if (MODE == MODE_NSEL) { ls0 = ((sel >> kt0) & 1ull) != 0ull; ls1 = ((sel >> (kt0 + 1)) & 1ull) != 0ull; }
;                 const unsigned long long b0 = __builtin_amdgcn_ballot_w64(ls0), b1 = __builtin_amdgcn_ballot_w64(ls1);
;                 if (b0 != 0ull && b1 != 0ull) {
;                     LAS char* K0 = lds + (sti & 1) * 4 * TILE_B;
;                     if ((b0 & b1) == ~0ull) tile128_pipe<0>(K0, K0 + TILE_B, K0 + 2 * TILE_B, K0 + 3 * TILE_B, qf, 1u, 1u, m1, l1, o1, r, h, lane);
;                     else tile128_pipe<1>(K0, K0 + TILE_B, K0 + 2 * TILE_B, K0 + 3 * TILE_B, qf, ls0 ? 1u : 0u, ls1 ? 1u : 0u, m1, l1, o1, r, h, lane);
;                     goto step_done;
.LBB0_849:
	s_lshl_b32 s62, s38, 1
	s_cmp_lt_u32 s62, s58
	s_cselect_b64 s[0:1], -1, 0
	s_lshl_b32 s10, s38, 7
	s_or_b32 s10, s10, 0x7f
	s_cmp_le_i32 s10, s27
	s_cselect_b64 s[10:11], -1, 0
	s_and_b64 s[0:1], s[0:1], s[10:11]
	s_andn2_b64 vcc, exec, s[0:1]
	s_mov_b32 s10, 0
	s_cbranch_vccnz .LBB0_872
	s_lshr_b32 s0, s38, 1
	v_lshrrev_b64 v[32:33], s0, v[168:169]
	v_and_b32_e32 v32, 1, v32
	v_cmp_eq_u32_e64 s[0:1], 1, v32
	v_cmp_ne_u32_e32 vcc, 0, v32
	s_cbranch_vccz .LBB0_872
	s_lshl_b32 s10, s38, 2
	s_and_b32 s10, s10, 4
	s_mulk_i32 s10, 0x2400
	s_add_i32 s10, s10, 0
	v_add_u32_e32 v32, s10, v184
	v_add_u32_e32 v192, v32, v160
	s_waitcnt lgkmcnt(7)
	ds_read_b128 v[140:143], v192
	s_waitcnt lgkmcnt(7)
	ds_read_b128 v[136:139], v192 offset:32
	s_waitcnt lgkmcnt(7)
	ds_read_b128 v[132:135], v192 offset:64
	s_waitcnt lgkmcnt(7)
	ds_read_b128 v[128:131], v192 offset:96
	s_cmp_lg_u64 vcc, -1
	s_setprio 1
	s_setprio 0
	s_waitcnt lgkmcnt(7)
	ds_read_b128 v[144:147], v192 offset:4608
	s_waitcnt lgkmcnt(7)
	ds_read_b128 v[148:151], v192 offset:4640
	s_waitcnt lgkmcnt(7)
	ds_read_b128 v[152:155], v192 offset:4672
	s_waitcnt lgkmcnt(7)
	ds_read_b128 v[156:159], v192 offset:4704
	s_setprio 1
	s_setprio 0
	v_add_f32_e32 v193, 0x41000000, v191
	s_cbranch_scc0 .LBB0_861
	s_waitcnt lgkmcnt(7)
	v_mfma_f32_32x32x16_bf16 v[32:47], v[140:143], v[112:115], 0
	s_waitcnt lgkmcnt(6)
	v_mfma_f32_32x32x16_bf16 v[32:47], v[136:139], v[116:119], v[32:47]
	s_waitcnt lgkmcnt(5)
	v_mfma_f32_32x32x16_bf16 v[32:47], v[132:135], v[120:123], v[32:47]
	s_waitcnt lgkmcnt(4)
	v_mfma_f32_32x32x16_bf16 v[32:47], v[128:131], v[124:127], v[32:47]
	s_waitcnt lgkmcnt(3)
	v_mfma_f32_32x32x16_bf16 v[64:79], v[144:147], v[112:115], 0
	s_nop 9
	v_max3_f32 v48, v32, s15, v33
	v_max3_f32 v48, v48, v34, v35
	v_max3_f32 v48, v48, v36, v37
	v_max3_f32 v48, v48, v38, v39
	v_max3_f32 v48, v48, v40, v41
	v_max3_f32 v48, v48, v42, v43
	v_max3_f32 v48, v48, v44, v45
	v_max3_f32 v48, v48, v46, v47
	v_cndmask_b32_e64 v48, v208, v48, s[0:1]
	v_mov_b32_e32 v49, v48
	v_mov_b32_e32 v50, v48
	s_nop 1
	v_permlane32_swap_b32_e32 v49, v50
	v_cndmask_b32_e64 v49, v49, v50, s[36:37]
	v_max_f32_e32 v49, v49, v49
	v_max_f32_e32 v48, v48, v49
	v_cmp_gt_f32_e32 vcc, v48, v193
	s_waitcnt lgkmcnt(2)
	v_mfma_f32_32x32x16_bf16 v[64:79], v[148:151], v[116:119], v[64:79]
	v_cndmask_b32_e32 v219, v191, v48, vcc
	v_max_f32_e32 v48, v219, v219
	v_max_f32_e32 v48, 0xefa18f08, v48
	v_cndmask_b32_e64 v48, v209, v48, s[0:1]
	v_sub_f32_e32 v32, v32, v48
	v_sub_f32_e32 v33, v33, v48
	v_exp_f32_e32 v80, v32
	v_sub_f32_e32 v34, v34, v48
	v_exp_f32_e32 v81, v33
	v_sub_f32_e32 v35, v35, v48
	v_exp_f32_e32 v82, v34
	v_sub_f32_e32 v36, v36, v48
	v_exp_f32_e32 v83, v35
	v_sub_f32_e32 v37, v37, v48
	v_exp_f32_e32 v84, v36
	v_add_f32_e32 v32, 0, v80
	v_sub_f32_e32 v38, v38, v48
	v_exp_f32_e32 v85, v37
	v_add_f32_e32 v32, v81, v32
	v_sub_f32_e32 v39, v39, v48
	v_exp_f32_e32 v86, v38
	s_waitcnt lgkmcnt(1)
	v_mfma_f32_32x32x16_bf16 v[64:79], v[152:155], v[120:123], v[64:79]
	v_add_f32_e32 v32, v82, v32
	v_sub_f32_e32 v40, v40, v48
	v_exp_f32_e32 v87, v39
	v_add_f32_e32 v32, v83, v32
	v_sub_f32_e32 v41, v41, v48
	v_exp_f32_e32 v88, v40
	v_add_f32_e32 v32, v84, v32
	v_sub_f32_e32 v42, v42, v48
	v_exp_f32_e32 v89, v41
	v_add_f32_e32 v32, v85, v32
	v_sub_f32_e32 v43, v43, v48
	v_exp_f32_e32 v90, v42
	v_add_f32_e32 v32, v86, v32
	v_sub_f32_e32 v44, v44, v48
	v_exp_f32_e32 v91, v43
	v_add_f32_e32 v32, v87, v32
	v_add_f32_e32 v32, v88, v32
	v_exp_f32_e32 v92, v44
	v_sub_f32_e32 v33, v45, v48
	v_add_f32_e32 v32, v89, v32
	v_exp_f32_e32 v93, v33
	v_sub_f32_e32 v33, v46, v48
	s_waitcnt lgkmcnt(0)
	v_mfma_f32_32x32x16_bf16 v[64:79], v[156:159], v[124:127], v[64:79]
	v_add_f32_e32 v32, v90, v32
	v_exp_f32_e32 v94, v33
	v_sub_f32_e32 v33, v47, v48
	v_add_f32_e32 v32, v91, v32
	v_exp_f32_e32 v95, v33
	v_add_f32_e32 v32, v92, v32
	v_sub_f32_e32 v49, v191, v219
	v_add_f32_e32 v32, v93, v32
	v_add_f32_e32 v32, v94, v32
	v_exp_f32_e32 v164, v49
	v_add_f32_e32 v212, v95, v32
	v_mov_b32_e32 v213, v212
	v_mov_b32_e32 v214, v212
	s_nop 0
	s_nop 0
	v_permlane32_swap_b32_e32 v213, v214
	v_cmp_neq_f32_e32 vcc, v219, v191
	s_cbranch_vccz .LBB0_854
	v_pk_mul_f32 v[30:31], v[30:31], v[164:165] op_sel_hi:[1,0]
	v_pk_mul_f32 v[28:29], v[28:29], v[164:165] op_sel_hi:[1,0]
	v_pk_mul_f32 v[26:27], v[26:27], v[164:165] op_sel_hi:[1,0]
	v_pk_mul_f32 v[24:25], v[24:25], v[164:165] op_sel_hi:[1,0]
	v_pk_mul_f32 v[22:23], v[22:23], v[164:165] op_sel_hi:[1,0]
	v_pk_mul_f32 v[20:21], v[20:21], v[164:165] op_sel_hi:[1,0]
	v_pk_mul_f32 v[18:19], v[18:19], v[164:165] op_sel_hi:[1,0]
	v_pk_mul_f32 v[16:17], v[16:17], v[164:165] op_sel_hi:[1,0]
	v_pk_mul_f32 v[14:15], v[14:15], v[164:165] op_sel_hi:[1,0]
	v_pk_mul_f32 v[12:13], v[12:13], v[164:165] op_sel_hi:[1,0]
	v_pk_mul_f32 v[10:11], v[10:11], v[164:165] op_sel_hi:[1,0]
	v_pk_mul_f32 v[8:9], v[8:9], v[164:165] op_sel_hi:[1,0]
	v_pk_mul_f32 v[6:7], v[6:7], v[164:165] op_sel_hi:[1,0]
	v_pk_mul_f32 v[4:5], v[4:5], v[164:165] op_sel_hi:[1,0]
	v_pk_mul_f32 v[2:3], v[2:3], v[164:165] op_sel_hi:[1,0]
	v_pk_mul_f32 v[0:1], v[0:1], v[164:165] op_sel_hi:[1,0]
; #define LAS __attribute__((address_space(3)))
; DI float ex2(float x) { return __builtin_amdgcn_exp2f(x); }
; template <int MM> DI void smax_step_nb(const f32x16& s, unsigned vm, float& m, float& l, f32x16 (&o)[2], bf16x8 (&pf)[2], int lane) {
;     float mx = -1e30f;
; #pragma unroll
;     for (int i = 0; i < 16; ++i) mx = fmaxf(mx, s[i]);
;     if (MM == 1) mx = vm ? mx : -1e30f;
;     mx = fmaxf(mx, shx32(mx, lane));
;     const float mn = (mx > m + 8.0f) ? mx : m;
;     float mref = fmaxf(mn, -1e29f);
;     if (MM == 1) mref = vm ? mref : 3e38f;
;     const float alpha = ex2(m - mn);
;     float p[16], rs = 0.f;
; #pragma unroll
;     for (int i = 0; i < 16; ++i) { p[i] = ex2(s[i] - mref); rs += p[i]; }
;     rs += shx32(rs, lane);
;     l = l * alpha + rs;
;     if (__builtin_amdgcn_ballot_w64(mn != m) != 0ull) {
; #pragma unroll
;         for (int i = 0; i < 16; ++i) { o[0][i] *= alpha; o[1][i] *= alpha; }
;     }
;     m = mn;
;     pack_p(p, pf);
; }
; template <int MM> DI void tile128_pipe(LAS const char* K0, LAS const char* V0, LAS const char* K1, LAS const char* V1, const bf16x8 (&qf)[4], unsigned vm0, unsigned vm1,
;                                        float& m, float& l, f32x16 (&o)[2], int r, int h, int lane) {
;     f32x16 sa = qk_rows<0, 4>(K0, 0, qf, r, h), sb = qk_rows<0, 4>(K0, 32, qf, r, h);
;     bf16x8 pfa[2], pfb[2];
;     smax_step_nb<MM>(sa, vm0, m, l, o, pfa, lane);
;     sa = qk_rows<0, 4>(K1, 0, qf, r, h);
;     pv_rows(o, V0, 0, pfa, lane);
;     smax_step_nb<MM>(sb, vm0, m, l, o, pfb, lane);
;     sb = qk_rows<0, 4>(K1, 32, qf, r, h);
;     pv_rows(o, V0, 32, pfb, lane);
;     smax_step_nb<MM>(sa, vm1, m, l, o, pfa, lane);
;     pv_rows(o, V1, 0, pfa, lane);
;     smax_step_nb<MM>(sb, vm1, m, l, o, pfb, lane);
;     pv_rows(o, V1, 32, pfb, lane);
; }
.LBB0_854:
	v_cvt_pk_bf16_f32 v220, v80, v81
	v_cvt_pk_bf16_f32 v221, v82, v83
	ds_read_b128 v[80:83], v192 offset:18432
	ds_read_b128 v[228:231], v192 offset:18464
	ds_read_b128 v[232:235], v192 offset:18496
	ds_read_b128 v[236:239], v192 offset:18528
	v_cvt_pk_bf16_f32 v222, v84, v85
	v_cvt_pk_bf16_f32 v223, v86, v87
	v_cvt_pk_bf16_f32 v224, v88, v89
	v_cvt_pk_bf16_f32 v225, v90, v91
	v_cvt_pk_bf16_f32 v226, v92, v93
	v_cvt_pk_bf16_f32 v227, v94, v95
	s_setprio 1
	s_waitcnt lgkmcnt(3)
	v_mfma_f32_32x32x16_bf16 v[80:95], v[80:83], v[112:115], 0
	s_waitcnt lgkmcnt(2)
	v_mfma_f32_32x32x16_bf16 v[80:95], v[228:231], v[116:119], v[80:95]
	s_waitcnt lgkmcnt(1)
	v_mfma_f32_32x32x16_bf16 v[80:95], v[232:235], v[120:123], v[80:95]
	s_waitcnt lgkmcnt(0)
	v_mfma_f32_32x32x16_bf16 v[80:95], v[236:239], v[124:127], v[80:95]
	s_setprio 0
	v_add3_u32 v166, s10, v186, v187
	v_add_u32_e32 v215, v166, v188
	ds_read_b64_tr_b16 v[228:229], v215 offset:9216
	ds_read_b64_tr_b16 v[230:231], v215 offset:10368
	ds_read_b64_tr_b16 v[234:235], v215 offset:10432
	ds_read_b64_tr_b16 v[232:233], v215 offset:9280
	ds_read_b64_tr_b16 v[236:237], v215 offset:11520
	ds_read_b64_tr_b16 v[238:239], v215 offset:12672
	ds_read_b64_tr_b16 v[242:243], v215 offset:12736
	ds_read_b64_tr_b16 v[240:241], v215 offset:11584
	s_setprio 1
	s_waitcnt lgkmcnt(6)
	v_mfma_f32_32x32x16_bf16 v[0:15], v[228:231], v[220:223], v[0:15]
	s_waitcnt lgkmcnt(4)
	v_mfma_f32_32x32x16_bf16 v[16:31], v[232:235], v[220:223], v[16:31]
	s_waitcnt lgkmcnt(2)
	v_mfma_f32_32x32x16_bf16 v[0:15], v[236:239], v[224:227], v[0:15]
	s_waitcnt lgkmcnt(0)
	v_mfma_f32_32x32x16_bf16 v[16:31], v[240:243], v[224:227], v[16:31]
	s_setprio 0
	v_max3_f32 v166, v64, s15, v65
	v_max3_f32 v166, v166, v66, v67
	v_max3_f32 v166, v166, v68, v69
	v_max3_f32 v166, v166, v70, v71
	v_max3_f32 v166, v166, v72, v73
	v_max3_f32 v166, v166, v74, v75
	v_max3_f32 v166, v166, v76, v77
	v_max3_f32 v166, v166, v78, v79
	v_cndmask_b32_e64 v166, v208, v166, s[0:1]
	v_mov_b32_e32 v172, v166
	v_mov_b32_e32 v173, v166
	s_nop 1
	v_permlane32_swap_b32_e32 v172, v173
	v_cndmask_b32_e64 v172, v172, v173, s[36:37]
	v_max_f32_e32 v172, v172, v172
	v_max_f32_e32 v166, v166, v172
	v_add_f32_e32 v172, 0x41000000, v219
	v_cmp_gt_f32_e32 vcc, v166, v172
	s_nop 1
	v_cndmask_b32_e32 v220, v219, v166, vcc
	v_max_f32_e32 v166, v220, v220
	v_max_f32_e32 v166, 0xefa18f08, v166
	v_cndmask_b32_e64 v166, v209, v166, s[0:1]
	v_sub_f32_e32 v64, v64, v166
	v_exp_f32_e32 v64, v64
	v_sub_f32_e32 v65, v65, v166
	v_exp_f32_e32 v65, v65
	v_sub_f32_e32 v66, v66, v166
	v_exp_f32_e32 v66, v66
	v_sub_f32_e32 v67, v67, v166
	v_exp_f32_e32 v67, v67
	v_sub_f32_e32 v68, v68, v166
	v_add_f32_e32 v173, 0, v64
	v_exp_f32_e32 v68, v68
	v_sub_f32_e32 v69, v69, v166
	v_add_f32_e32 v173, v65, v173
	v_exp_f32_e32 v69, v69
	v_sub_f32_e32 v70, v70, v166
	v_add_f32_e32 v173, v66, v173
	v_exp_f32_e32 v70, v70
	v_sub_f32_e32 v71, v71, v166
	v_add_f32_e32 v173, v67, v173
	v_exp_f32_e32 v71, v71
	v_sub_f32_e32 v72, v72, v166
	v_add_f32_e32 v173, v68, v173
	v_exp_f32_e32 v72, v72
	v_sub_f32_e32 v73, v73, v166
	v_add_f32_e32 v173, v69, v173
	v_exp_f32_e32 v73, v73
	v_sub_f32_e32 v74, v74, v166
	v_add_f32_e32 v173, v70, v173
	v_exp_f32_e32 v74, v74
	v_sub_f32_e32 v75, v75, v166
	v_add_f32_e32 v173, v71, v173
	v_exp_f32_e32 v75, v75
	v_sub_f32_e32 v76, v76, v166
	v_add_f32_e32 v173, v72, v173
	v_exp_f32_e32 v76, v76
	v_sub_f32_e32 v77, v77, v166
	v_add_f32_e32 v173, v73, v173
	v_exp_f32_e32 v77, v77
	v_sub_f32_e32 v78, v78, v166
	v_add_f32_e32 v173, v74, v173
	v_exp_f32_e32 v78, v78
	v_sub_f32_e32 v79, v79, v166
	v_add_f32_e32 v173, v75, v173
	v_exp_f32_e32 v79, v79
	v_add_f32_e32 v166, v76, v173
	v_add_f32_e32 v166, v77, v166
	v_sub_f32_e32 v172, v219, v220
	v_add_f32_e32 v166, v78, v166
	v_add_f32_e32 v216, v79, v166
	v_exp_f32_e32 v166, v172
	v_mov_b32_e32 v217, v216
	v_mov_b32_e32 v218, v216
	s_nop 1
	v_permlane32_swap_b32_e32 v217, v218
	v_cmp_neq_f32_e32 vcc, v220, v219
	s_cbranch_vccz .LBB0_856
	v_pk_mul_f32 v[30:31], v[30:31], v[166:167] op_sel_hi:[1,0]
	v_pk_mul_f32 v[28:29], v[28:29], v[166:167] op_sel_hi:[1,0]
	v_pk_mul_f32 v[26:27], v[26:27], v[166:167] op_sel_hi:[1,0]
	v_pk_mul_f32 v[24:25], v[24:25], v[166:167] op_sel_hi:[1,0]
	v_pk_mul_f32 v[22:23], v[22:23], v[166:167] op_sel_hi:[1,0]
	v_pk_mul_f32 v[20:21], v[20:21], v[166:167] op_sel_hi:[1,0]
	v_pk_mul_f32 v[18:19], v[18:19], v[166:167] op_sel_hi:[1,0]
	v_pk_mul_f32 v[16:17], v[16:17], v[166:167] op_sel_hi:[1,0]
	v_pk_mul_f32 v[14:15], v[14:15], v[166:167] op_sel_hi:[1,0]
	v_pk_mul_f32 v[12:13], v[12:13], v[166:167] op_sel_hi:[1,0]
	v_pk_mul_f32 v[10:11], v[10:11], v[166:167] op_sel_hi:[1,0]
	v_pk_mul_f32 v[8:9], v[8:9], v[166:167] op_sel_hi:[1,0]
	v_pk_mul_f32 v[6:7], v[6:7], v[166:167] op_sel_hi:[1,0]
	v_pk_mul_f32 v[4:5], v[4:5], v[166:167] op_sel_hi:[1,0]
	v_pk_mul_f32 v[2:3], v[2:3], v[166:167] op_sel_hi:[1,0]
	v_pk_mul_f32 v[0:1], v[0:1], v[166:167] op_sel_hi:[1,0]
; #define LAS __attribute__((address_space(3)))
; DI float ex2(float x) { return __builtin_amdgcn_exp2f(x); }
; template <int MM> DI void smax_step_nb(const f32x16& s, unsigned vm, float& m, float& l, f32x16 (&o)[2], bf16x8 (&pf)[2], int lane) {
;     float mx = -1e30f;
; #pragma unroll
;     for (int i = 0; i < 16; ++i) mx = fmaxf(mx, s[i]);
;     if (MM == 1) mx = vm ? mx : -1e30f;
;     mx = fmaxf(mx, shx32(mx, lane));
;     const float mn = (mx > m + 8.0f) ? mx : m;
;     float mref = fmaxf(mn, -1e29f);
;     if (MM == 1) mref = vm ? mref : 3e38f;
;     const float alpha = ex2(m - mn);
;     float p[16], rs = 0.f;
; #pragma unroll
;     for (int i = 0; i < 16; ++i) { p[i] = ex2(s[i] - mref); rs += p[i]; }
;     rs += shx32(rs, lane);
;     l = l * alpha + rs;
;     if (__builtin_amdgcn_ballot_w64(mn != m) != 0ull) {
; #pragma unroll
;         for (int i = 0; i < 16; ++i) { o[0][i] *= alpha; o[1][i] *= alpha; }
;     }
;     m = mn;
;     pack_p(p, pf);
; }
; template <int MM> DI void tile128_pipe(LAS const char* K0, LAS const char* V0, LAS const char* K1, LAS const char* V1, const bf16x8 (&qf)[4], unsigned vm0, unsigned vm1,
;                                        float& m, float& l, f32x16 (&o)[2], int r, int h, int lane) {
;     f32x16 sa = qk_rows<0, 4>(K0, 0, qf, r, h), sb = qk_rows<0, 4>(K0, 32, qf, r, h);
;     bf16x8 pfa[2], pfb[2];
;     smax_step_nb<MM>(sa, vm0, m, l, o, pfa, lane);
;     sa = qk_rows<0, 4>(K1, 0, qf, r, h);
;     pv_rows(o, V0, 0, pfa, lane);
;     smax_step_nb<MM>(sb, vm0, m, l, o, pfb, lane);
;     sb = qk_rows<0, 4>(K1, 32, qf, r, h);
;     pv_rows(o, V0, 32, pfb, lane);
;     smax_step_nb<MM>(sa, vm1, m, l, o, pfa, lane);
;     pv_rows(o, V1, 0, pfa, lane);
;     smax_step_nb<MM>(sb, vm1, m, l, o, pfb, lane);
;     pv_rows(o, V1, 32, pfb, lane);
; }
.LBB0_856:
	v_cvt_pk_bf16_f32 v222, v64, v65
	v_cvt_pk_bf16_f32 v223, v66, v67
	ds_read_b128 v[64:67], v192 offset:23040
	ds_read_b128 v[230:233], v192 offset:23072
	ds_read_b128 v[234:237], v192 offset:23104
	ds_read_b128 v[238:241], v192 offset:23136
	v_cvt_pk_bf16_f32 v224, v68, v69
	v_cvt_pk_bf16_f32 v225, v70, v71
	v_cvt_pk_bf16_f32 v226, v72, v73
	v_cvt_pk_bf16_f32 v227, v74, v75
	v_cvt_pk_bf16_f32 v228, v76, v77
	v_cvt_pk_bf16_f32 v229, v78, v79
	s_setprio 1
	s_waitcnt lgkmcnt(3)
	v_mfma_f32_32x32x16_bf16 v[64:79], v[64:67], v[112:115], 0
	s_waitcnt lgkmcnt(2)
	v_mfma_f32_32x32x16_bf16 v[64:79], v[230:233], v[116:119], v[64:79]
	s_waitcnt lgkmcnt(1)
	v_mfma_f32_32x32x16_bf16 v[64:79], v[234:237], v[120:123], v[64:79]
	s_waitcnt lgkmcnt(0)
	v_mfma_f32_32x32x16_bf16 v[64:79], v[238:241], v[124:127], v[64:79]
	s_setprio 0
	ds_read_b64_tr_b16 v[230:231], v215 offset:13824
	ds_read_b64_tr_b16 v[232:233], v215 offset:14976
	ds_read_b64_tr_b16 v[236:237], v215 offset:15040
	ds_read_b64_tr_b16 v[234:235], v215 offset:13888
	ds_read_b64_tr_b16 v[238:239], v215 offset:16128
	ds_read_b64_tr_b16 v[240:241], v215 offset:17280
	ds_read_b64_tr_b16 v[244:245], v215 offset:17344
	ds_read_b64_tr_b16 v[242:243], v215 offset:16192
	s_setprio 1
	s_waitcnt lgkmcnt(6)
	v_mfma_f32_32x32x16_bf16 v[0:15], v[230:233], v[222:225], v[0:15]
	s_waitcnt lgkmcnt(4)
	v_mfma_f32_32x32x16_bf16 v[16:31], v[234:237], v[222:225], v[16:31]
	s_waitcnt lgkmcnt(2)
	v_mfma_f32_32x32x16_bf16 v[0:15], v[238:241], v[226:229], v[0:15]
	s_waitcnt lgkmcnt(0)
	v_mfma_f32_32x32x16_bf16 v[16:31], v[242:245], v[226:229], v[16:31]
	s_setprio 0
	v_max3_f32 v172, v80, s15, v81
	v_max3_f32 v172, v172, v82, v83
	v_max3_f32 v172, v172, v84, v85
	v_max3_f32 v172, v172, v86, v87
	v_max3_f32 v172, v172, v88, v89
	v_max3_f32 v172, v172, v90, v91
	v_max3_f32 v172, v172, v92, v93
	v_max3_f32 v172, v172, v94, v95
	v_cndmask_b32_e64 v172, v208, v172, s[0:1]
	v_mov_b32_e32 v173, v172
	v_mov_b32_e32 v206, v172
	s_nop 1
	v_permlane32_swap_b32_e32 v173, v206
	v_cndmask_b32_e64 v173, v173, v206, s[36:37]
	v_max_f32_e32 v173, v173, v173
	v_max_f32_e32 v172, v172, v173
	v_add_f32_e32 v173, 0x41000000, v220
	v_cmp_gt_f32_e32 vcc, v172, v173
	s_nop 1
	v_cndmask_b32_e32 v219, v220, v172, vcc
	v_max_f32_e32 v172, v219, v219
	v_max_f32_e32 v172, 0xefa18f08, v172
	v_cndmask_b32_e64 v172, v209, v172, s[0:1]
	v_sub_f32_e32 v80, v80, v172
	v_exp_f32_e32 v221, v80
	v_sub_f32_e32 v80, v81, v172
	v_exp_f32_e32 v81, v80
	v_sub_f32_e32 v80, v82, v172
	v_exp_f32_e32 v222, v80
	v_sub_f32_e32 v80, v83, v172
	v_exp_f32_e32 v223, v80
	v_sub_f32_e32 v82, v84, v172
	v_add_f32_e32 v80, 0, v221
	v_exp_f32_e32 v224, v82
	v_sub_f32_e32 v82, v85, v172
	v_add_f32_e32 v80, v81, v80
	v_exp_f32_e32 v85, v82
	v_sub_f32_e32 v82, v86, v172
	v_add_f32_e32 v80, v222, v80
	v_exp_f32_e32 v86, v82
	v_sub_f32_e32 v82, v87, v172
	v_add_f32_e32 v80, v223, v80
	v_exp_f32_e32 v87, v82
	v_sub_f32_e32 v82, v88, v172
	v_add_f32_e32 v80, v224, v80
	v_exp_f32_e32 v88, v82
	v_sub_f32_e32 v82, v89, v172
	v_add_f32_e32 v80, v85, v80
	v_exp_f32_e32 v89, v82
	v_sub_f32_e32 v82, v90, v172
	v_add_f32_e32 v80, v86, v80
	v_exp_f32_e32 v90, v82
	v_sub_f32_e32 v82, v91, v172
	v_add_f32_e32 v80, v87, v80
	v_exp_f32_e32 v91, v82
	v_sub_f32_e32 v82, v92, v172
	v_add_f32_e32 v80, v88, v80
	v_exp_f32_e32 v92, v82
	v_sub_f32_e32 v82, v93, v172
	v_add_f32_e32 v80, v89, v80
	v_exp_f32_e32 v93, v82
	v_sub_f32_e32 v82, v94, v172
	v_add_f32_e32 v80, v90, v80
	v_exp_f32_e32 v94, v82
	v_sub_f32_e32 v82, v95, v172
	v_add_f32_e32 v80, v91, v80
	v_exp_f32_e32 v95, v82
	v_add_f32_e32 v80, v92, v80
	v_add_f32_e32 v80, v93, v80
	v_sub_f32_e32 v173, v220, v219
	v_add_f32_e32 v80, v94, v80
	v_add_f32_e32 v82, v95, v80
	v_exp_f32_e32 v80, v173
	v_mov_b32_e32 v83, v82
	v_mov_b32_e32 v84, v82
	s_nop 1
	v_permlane32_swap_b32_e32 v83, v84
	v_cmp_neq_f32_e32 vcc, v219, v220
	s_cbranch_vccz .LBB0_858
	v_pk_mul_f32 v[30:31], v[30:31], v[80:81] op_sel_hi:[1,0]
	v_pk_mul_f32 v[28:29], v[28:29], v[80:81] op_sel_hi:[1,0]
	v_pk_mul_f32 v[26:27], v[26:27], v[80:81] op_sel_hi:[1,0]
	v_pk_mul_f32 v[24:25], v[24:25], v[80:81] op_sel_hi:[1,0]
	v_pk_mul_f32 v[22:23], v[22:23], v[80:81] op_sel_hi:[1,0]
	v_pk_mul_f32 v[20:21], v[20:21], v[80:81] op_sel_hi:[1,0]
	v_pk_mul_f32 v[18:19], v[18:19], v[80:81] op_sel_hi:[1,0]
	v_pk_mul_f32 v[16:17], v[16:17], v[80:81] op_sel_hi:[1,0]
	v_pk_mul_f32 v[14:15], v[14:15], v[80:81] op_sel_hi:[1,0]
	v_pk_mul_f32 v[12:13], v[12:13], v[80:81] op_sel_hi:[1,0]
	v_pk_mul_f32 v[10:11], v[10:11], v[80:81] op_sel_hi:[1,0]
	v_pk_mul_f32 v[8:9], v[8:9], v[80:81] op_sel_hi:[1,0]
	v_pk_mul_f32 v[6:7], v[6:7], v[80:81] op_sel_hi:[1,0]
	v_pk_mul_f32 v[4:5], v[4:5], v[80:81] op_sel_hi:[1,0]
	v_pk_mul_f32 v[2:3], v[2:3], v[80:81] op_sel_hi:[1,0]
	v_pk_mul_f32 v[0:1], v[0:1], v[80:81] op_sel_hi:[1,0]
; #define LAS __attribute__((address_space(3)))
; DI float ex2(float x) { return __builtin_amdgcn_exp2f(x); }
; template <int MM> DI void smax_step_nb(const f32x16& s, unsigned vm, float& m, float& l, f32x16 (&o)[2], bf16x8 (&pf)[2], int lane) {
;     float mx = -1e30f;
; #pragma unroll
;     for (int i = 0; i < 16; ++i) mx = fmaxf(mx, s[i]);
;     if (MM == 1) mx = vm ? mx : -1e30f;
;     mx = fmaxf(mx, shx32(mx, lane));
;     const float mn = (mx > m + 8.0f) ? mx : m;
;     float mref = fmaxf(mn, -1e29f);
;     if (MM == 1) mref = vm ? mref : 3e38f;
;     const float alpha = ex2(m - mn);
;     float p[16], rs = 0.f;
; #pragma unroll
;     for (int i = 0; i < 16; ++i) { p[i] = ex2(s[i] - mref); rs += p[i]; }
;     rs += shx32(rs, lane);
;     l = l * alpha + rs;
;     if (__builtin_amdgcn_ballot_w64(mn != m) != 0ull) {
; #pragma unroll
;         for (int i = 0; i < 16; ++i) { o[0][i] *= alpha; o[1][i] *= alpha; }
;     }
;     m = mn;
;     pack_p(p, pf);
; }
; template <int MM> DI void tile128_pipe(LAS const char* K0, LAS const char* V0, LAS const char* K1, LAS const char* V1, const bf16x8 (&qf)[4], unsigned vm0, unsigned vm1,
;                                        float& m, float& l, f32x16 (&o)[2], int r, int h, int lane) {
;     f32x16 sa = qk_rows<0, 4>(K0, 0, qf, r, h), sb = qk_rows<0, 4>(K0, 32, qf, r, h);
;     bf16x8 pfa[2], pfb[2];
;     smax_step_nb<MM>(sa, vm0, m, l, o, pfa, lane);
;     sa = qk_rows<0, 4>(K1, 0, qf, r, h);
;     pv_rows(o, V0, 0, pfa, lane);
;     smax_step_nb<MM>(sb, vm0, m, l, o, pfb, lane);
;     sb = qk_rows<0, 4>(K1, 32, qf, r, h);
;     pv_rows(o, V0, 32, pfb, lane);
;     smax_step_nb<MM>(sa, vm1, m, l, o, pfa, lane);
;     pv_rows(o, V1, 0, pfa, lane);
;     smax_step_nb<MM>(sb, vm1, m, l, o, pfb, lane);
;     pv_rows(o, V1, 32, pfb, lane);
; }
.LBB0_858:
	v_cvt_pk_bf16_f32 v220, v221, v81
	v_cvt_pk_bf16_f32 v221, v222, v223
	v_cvt_pk_bf16_f32 v222, v224, v85
	v_cvt_pk_bf16_f32 v223, v86, v87
	v_cvt_pk_bf16_f32 v86, v88, v89
	v_cvt_pk_bf16_f32 v87, v90, v91
	v_cvt_pk_bf16_f32 v88, v92, v93
	ds_read_b64_tr_b16 v[90:91], v215 offset:27648
	ds_read_b64_tr_b16 v[92:93], v215 offset:28800
	ds_read_b64_tr_b16 v[224:225], v215 offset:29952
	ds_read_b64_tr_b16 v[226:227], v215 offset:31104
	ds_read_b64_tr_b16 v[228:229], v215 offset:27712
	ds_read_b64_tr_b16 v[230:231], v215 offset:28864
	ds_read_b64_tr_b16 v[232:233], v215 offset:30016
	ds_read_b64_tr_b16 v[234:235], v215 offset:31168
	v_cvt_pk_bf16_f32 v89, v94, v95
	s_setprio 1
	s_waitcnt lgkmcnt(6)
	v_mfma_f32_32x32x16_bf16 v[0:15], v[90:93], v[220:223], v[0:15]
	s_waitcnt lgkmcnt(2)
	v_mfma_f32_32x32x16_bf16 v[16:31], v[228:231], v[220:223], v[16:31]
	v_mfma_f32_32x32x16_bf16 v[0:15], v[224:227], v[86:89], v[0:15]
	s_waitcnt lgkmcnt(0)
	v_mfma_f32_32x32x16_bf16 v[16:31], v[232:235], v[86:89], v[16:31]
	s_setprio 0
	v_max3_f32 v81, v64, s15, v65
	v_max3_f32 v81, v81, v66, v67
	v_max3_f32 v81, v81, v68, v69
	v_max3_f32 v81, v81, v70, v71
	v_max3_f32 v81, v81, v72, v73
	v_max3_f32 v81, v81, v74, v75
	v_max3_f32 v81, v81, v76, v77
	v_max3_f32 v81, v81, v78, v79
	v_cndmask_b32_e64 v81, v208, v81, s[0:1]
	v_mov_b32_e32 v85, v81
	v_mov_b32_e32 v86, v81
	s_nop 1
	v_permlane32_swap_b32_e32 v85, v86
	v_cndmask_b32_e64 v85, v85, v86, s[36:37]
	v_max_f32_e32 v85, v85, v85
	v_max_f32_e32 v81, v81, v85
	v_add_f32_e32 v85, 0x41000000, v219
	v_cmp_gt_f32_e32 vcc, v81, v85
	s_nop 1
	v_cndmask_b32_e32 v81, v219, v81, vcc
	v_max_f32_e32 v85, v81, v81
	v_max_f32_e32 v85, 0xefa18f08, v85
	v_cndmask_b32_e64 v93, v209, v85, s[0:1]
	v_sub_f32_e32 v64, v64, v93
	v_exp_f32_e32 v85, v64
	v_sub_f32_e32 v64, v65, v93
	v_exp_f32_e32 v86, v64
	v_sub_f32_e32 v64, v66, v93
	v_exp_f32_e32 v87, v64
	v_sub_f32_e32 v64, v67, v93
	v_exp_f32_e32 v88, v64
	v_sub_f32_e32 v65, v68, v93
	v_add_f32_e32 v64, 0, v85
	v_exp_f32_e32 v89, v65
	v_sub_f32_e32 v65, v69, v93
	v_add_f32_e32 v64, v86, v64
	v_exp_f32_e32 v90, v65
	v_sub_f32_e32 v65, v70, v93
	v_add_f32_e32 v64, v87, v64
	v_exp_f32_e32 v91, v65
	v_sub_f32_e32 v65, v71, v93
	v_add_f32_e32 v64, v88, v64
	v_exp_f32_e32 v92, v65
	v_sub_f32_e32 v65, v72, v93
	v_add_f32_e32 v64, v89, v64
	v_exp_f32_e32 v66, v65
	v_sub_f32_e32 v65, v73, v93
	v_add_f32_e32 v64, v90, v64
	v_exp_f32_e32 v67, v65
	v_sub_f32_e32 v65, v74, v93
	v_add_f32_e32 v64, v91, v64
	v_exp_f32_e32 v68, v65
	v_sub_f32_e32 v65, v75, v93
	v_add_f32_e32 v64, v92, v64
	v_exp_f32_e32 v69, v65
	v_sub_f32_e32 v65, v76, v93
	v_add_f32_e32 v64, v66, v64
	v_exp_f32_e32 v70, v65
	v_sub_f32_e32 v65, v77, v93
	v_add_f32_e32 v64, v67, v64
	v_exp_f32_e32 v71, v65
	v_sub_f32_e32 v65, v78, v93
	v_add_f32_e32 v64, v68, v64
	v_exp_f32_e32 v72, v65
	v_sub_f32_e32 v65, v79, v93
	v_add_f32_e32 v64, v69, v64
	v_exp_f32_e32 v73, v65
	v_add_f32_e32 v64, v70, v64
	v_add_f32_e32 v64, v71, v64
	v_sub_f32_e32 v94, v219, v81
	v_add_f32_e32 v64, v72, v64
	v_add_f32_e32 v65, v73, v64
	v_exp_f32_e32 v64, v94
	v_mov_b32_e32 v74, v65
	v_mov_b32_e32 v75, v65
	s_nop 1
	v_permlane32_swap_b32_e32 v74, v75
	v_cmp_neq_f32_e32 vcc, v81, v219
	s_cbranch_vccz .LBB0_860
	v_pk_mul_f32 v[30:31], v[30:31], v[64:65] op_sel_hi:[1,0]
	v_pk_mul_f32 v[28:29], v[28:29], v[64:65] op_sel_hi:[1,0]
	v_pk_mul_f32 v[26:27], v[26:27], v[64:65] op_sel_hi:[1,0]
	v_pk_mul_f32 v[24:25], v[24:25], v[64:65] op_sel_hi:[1,0]
	v_pk_mul_f32 v[22:23], v[22:23], v[64:65] op_sel_hi:[1,0]
	v_pk_mul_f32 v[20:21], v[20:21], v[64:65] op_sel_hi:[1,0]
	v_pk_mul_f32 v[18:19], v[18:19], v[64:65] op_sel_hi:[1,0]
	v_pk_mul_f32 v[16:17], v[16:17], v[64:65] op_sel_hi:[1,0]
	v_pk_mul_f32 v[14:15], v[14:15], v[64:65] op_sel_hi:[1,0]
	v_pk_mul_f32 v[12:13], v[12:13], v[64:65] op_sel_hi:[1,0]
	v_pk_mul_f32 v[10:11], v[10:11], v[64:65] op_sel_hi:[1,0]
	v_pk_mul_f32 v[8:9], v[8:9], v[64:65] op_sel_hi:[1,0]
	v_pk_mul_f32 v[6:7], v[6:7], v[64:65] op_sel_hi:[1,0]
	v_pk_mul_f32 v[4:5], v[4:5], v[64:65] op_sel_hi:[1,0]
	v_pk_mul_f32 v[2:3], v[2:3], v[64:65] op_sel_hi:[1,0]
	v_pk_mul_f32 v[0:1], v[0:1], v[64:65] op_sel_hi:[1,0]
.LBB0_860:
	v_cndmask_b32_e64 v76, v213, v214, s[36:37]
	v_add_f32_e32 v76, v212, v76
	v_cndmask_b32_e64 v77, v217, v218, s[36:37]
	v_fmac_f32_e32 v76, v190, v164
	v_add_f32_e32 v77, v216, v77
	v_fmac_f32_e32 v77, v76, v166
	v_cndmask_b32_e64 v76, v83, v84, s[36:37]
	v_add_f32_e32 v76, v82, v76
	v_cndmask_b32_e64 v74, v74, v75, s[36:37]
	v_fmac_f32_e32 v76, v77, v80
	v_add_f32_e32 v65, v65, v74
	v_fmac_f32_e32 v65, v76, v64
	v_cvt_pk_bf16_f32 v74, v85, v86
	v_cvt_pk_bf16_f32 v75, v87, v88
	v_cvt_pk_bf16_f32 v76, v89, v90
	v_cvt_pk_bf16_f32 v77, v91, v92
	ds_read_b64_tr_b16 v[84:85], v215 offset:33408
	ds_read_b64_tr_b16 v[86:87], v215 offset:34560
	ds_read_b64_tr_b16 v[90:91], v215 offset:34624
	ds_read_b64_tr_b16 v[218:219], v215 offset:33472
	ds_read_b64_tr_b16 v[82:83], v215 offset:32256
	ds_read_b64_tr_b16 v[88:89], v215 offset:35712
	ds_read_b64_tr_b16 v[216:217], v215 offset:32320
	ds_read_b64_tr_b16 v[92:93], v215 offset:35776
	v_cvt_pk_bf16_f32 v66, v66, v67
	v_cvt_pk_bf16_f32 v67, v68, v69
	v_cvt_pk_bf16_f32 v68, v70, v71
	v_cvt_pk_bf16_f32 v69, v72, v73
	s_setprio 1
	s_waitcnt lgkmcnt(3)
	v_mfma_f32_32x32x16_bf16 v[0:15], v[82:85], v[74:77], v[0:15]
	s_waitcnt lgkmcnt(1)
	v_mfma_f32_32x32x16_bf16 v[16:31], v[216:219], v[74:77], v[16:31]
	v_mfma_f32_32x32x16_bf16 v[0:15], v[86:89], v[66:69], v[0:15]
	s_waitcnt lgkmcnt(0)
	v_mfma_f32_32x32x16_bf16 v[16:31], v[90:93], v[66:69], v[16:31]
	s_branch .LBB0_871

; #define LAS __attribute__((address_space(3)))
; template <int MODE, bool PRE = false> ...
;     ...
;                 if (b0 != 0ull && b1 != 0ull) {
;                     LAS char* K0 = lds + (sti & 1) * 4 * TILE_B;
;                     if ((b0 & b1) == ~0ull) tile128_pipe<0>(K0, K0 + TILE_B, K0 + 2 * TILE_B, K0 + 3 * TILE_B, qf, 1u, 1u, m1, l1, o1, r, h, lane);
;                     else tile128_pipe<1>(K0, K0 + TILE_B, K0 + 2 * TILE_B, K0 + 3 * TILE_B, qf, ls0 ? 1u : 0u, ls1 ? 1u : 0u, m1, l1, o1, r, h, lane);
;                     goto step_done;
;                 }
.LBB0_871:
	s_setprio 0
	s_mov_b32 s10, 9
	v_mov_b32_e32 v191, v81
	v_mov_b32_e32 v190, v65
